# same-accumulator MFMA pairs issued back-to-back in all live bf16 K-loops (SrcC forwarding), on top of local barriers, early invalidate and PV wait fix
# speedup vs baseline: 1.0124x; 1.0059x over previous
.LBB0_1516:
	v_add_u32_e32 v156, s83, v142
	v_add_u32_e32 v172, s44, v142
	s_add_u32 s8, s37, s6
	ds_read_b128 v[144:147], v156
	ds_read_b128 v[148:151], v156 offset:1024
	ds_read_b128 v[152:155], v156 offset:2048
	ds_read_b128 v[156:159], v156 offset:3072
	ds_read_b128 v[160:163], v172
	ds_read_b128 v[164:167], v172 offset:1024
	ds_read_b128 v[168:171], v172 offset:2048
	ds_read_b128 v[172:175], v172 offset:3072
	s_addc_u32 s9, s40, s7
	s_add_u32 s8, s8, 0x20400100
	s_addc_u32 s9, s9, 0
	s_add_u32 s46, s41, s6
	s_addc_u32 s47, s42, s7
	s_cmpk_eq_i32 s6, 0xf00
	s_cselect_b32 s11, s5, s9
	s_cselect_b32 s10, s4, s8
	s_cselect_b32 s9, s3, s47
	s_cselect_b32 s8, s2, s46
	v_lshl_add_u64 v[208:209], v[138:139], 0, s[6:7]
	s_add_i32 m0, s16, 0xc000
	ds_read_b128 v[176:179], v143
	ds_read_b128 v[180:183], v143 offset:1024
	ds_read_b128 v[184:187], v143 offset:2048
	ds_read_b128 v[188:191], v143 offset:3072
	ds_read_b128 v[192:195], v143 offset:4096
	ds_read_b128 v[196:199], v143 offset:5120
	ds_read_b128 v[200:203], v143 offset:6144
	ds_read_b128 v[204:207], v143 offset:7168
	global_load_lds_dwordx4 v[208:209], off
	v_lshl_add_u64 v[208:209], v[140:141], 0, s[6:7]
	s_add_i32 m0, s16, 0xe000
	s_nop 0
	global_load_lds_dwordx4 v[208:209], off
	s_waitcnt vmcnt(8)
	s_waitcnt lgkmcnt(0)
	s_barrier
	s_setprio 1
	s_waitcnt lgkmcnt(0)
	v_mfma_f32_16x16x32_bf16 v[128:131], v[144:147], v[176:179], v[128:131]
	v_mfma_f32_16x16x32_bf16 v[128:131], v[148:151], v[180:183], v[128:131]
	v_mfma_f32_16x16x32_bf16 v[124:127], v[152:155], v[176:179], v[124:127]
	v_mfma_f32_16x16x32_bf16 v[124:127], v[156:159], v[180:183], v[124:127]
	v_mfma_f32_16x16x32_bf16 v[112:115], v[144:147], v[184:187], v[112:115]
	v_mfma_f32_16x16x32_bf16 v[112:115], v[148:151], v[188:191], v[112:115]
	v_mfma_f32_16x16x32_bf16 v[108:111], v[152:155], v[184:187], v[108:111]
	v_mfma_f32_16x16x32_bf16 v[108:111], v[156:159], v[188:191], v[108:111]
	v_mfma_f32_16x16x32_bf16 v[96:99], v[144:147], v[192:195], v[96:99]
	v_mfma_f32_16x16x32_bf16 v[96:99], v[148:151], v[196:199], v[96:99]
	v_mfma_f32_16x16x32_bf16 v[92:95], v[152:155], v[192:195], v[92:95]
	v_mfma_f32_16x16x32_bf16 v[92:95], v[156:159], v[196:199], v[92:95]
	v_mfma_f32_16x16x32_bf16 v[80:83], v[144:147], v[200:203], v[80:83]
	v_mfma_f32_16x16x32_bf16 v[80:83], v[148:151], v[204:207], v[80:83]
	v_mfma_f32_16x16x32_bf16 v[76:79], v[152:155], v[200:203], v[76:79]
	v_mfma_f32_16x16x32_bf16 v[76:79], v[156:159], v[204:207], v[76:79]
	s_setprio 0
	s_setprio 1
	v_mfma_f32_16x16x32_bf16 v[120:123], v[160:163], v[176:179], v[120:123]
	v_mfma_f32_16x16x32_bf16 v[120:123], v[164:167], v[180:183], v[120:123]
	v_mfma_f32_16x16x32_bf16 v[116:119], v[168:171], v[176:179], v[116:119]
	v_mfma_f32_16x16x32_bf16 v[116:119], v[172:175], v[180:183], v[116:119]
	v_mfma_f32_16x16x32_bf16 v[104:107], v[160:163], v[184:187], v[104:107]
	v_mfma_f32_16x16x32_bf16 v[104:107], v[164:167], v[188:191], v[104:107]
	v_mfma_f32_16x16x32_bf16 v[100:103], v[168:171], v[184:187], v[100:103]
	v_mfma_f32_16x16x32_bf16 v[100:103], v[172:175], v[188:191], v[100:103]
	v_mfma_f32_16x16x32_bf16 v[88:91], v[160:163], v[192:195], v[88:91]
	v_mfma_f32_16x16x32_bf16 v[88:91], v[164:167], v[196:199], v[88:91]
	v_mfma_f32_16x16x32_bf16 v[84:87], v[168:171], v[192:195], v[84:87]
	v_mfma_f32_16x16x32_bf16 v[84:87], v[172:175], v[196:199], v[84:87]
	v_mfma_f32_16x16x32_bf16 v[72:75], v[160:163], v[200:203], v[72:75]
	v_mfma_f32_16x16x32_bf16 v[72:75], v[164:167], v[204:207], v[72:75]
	v_mfma_f32_16x16x32_bf16 v[68:71], v[168:171], v[200:203], v[68:71]
	v_mfma_f32_16x16x32_bf16 v[68:71], v[172:175], v[204:207], v[68:71]
	s_setprio 0
	s_barrier
	s_mov_b32 m0, s13
	v_lshl_add_u64 v[208:209], s[8:9], 0, v[2:3]
	s_add_u32 s46, s8, 0x80000
	ds_read_b128 v[176:179], v143 offset:16384
	ds_read_b128 v[180:183], v143 offset:17408
	ds_read_b128 v[184:187], v143 offset:18432
	ds_read_b128 v[188:191], v143 offset:19456
	ds_read_b128 v[192:195], v143 offset:20480
	ds_read_b128 v[196:199], v143 offset:21504
	ds_read_b128 v[200:203], v143 offset:22528
	ds_read_b128 v[204:207], v143 offset:23552
	global_load_lds_dwordx4 v[208:209], off
	v_lshl_add_u64 v[210:211], s[8:9], 0, v[136:137]
	s_mov_b32 m0, s14
	s_addc_u32 s47, s9, 0
	global_load_lds_dwordx4 v[210:211], off
	v_lshl_add_u64 v[216:217], s[46:47], 0, v[2:3]
	s_mov_b32 m0, s15
	v_lshl_add_u64 v[218:219], s[10:11], 0, v[134:135]
	global_load_lds_dwordx4 v[216:217], off
	v_lshl_add_u64 v[216:217], s[46:47], 0, v[136:137]
	s_mov_b32 m0, s19
	s_nop 0
	global_load_lds_dwordx4 v[216:217], off
	v_lshl_add_u64 v[216:217], s[10:11], 0, v[132:133]
	s_mov_b32 m0, s16
	s_nop 0
	global_load_lds_dwordx4 v[216:217], off
	s_mov_b32 m0, s20
	s_nop 0
	global_load_lds_dwordx4 v[218:219], off
	s_waitcnt vmcnt(8)
	s_waitcnt lgkmcnt(0)
	s_barrier
	s_setprio 1
	s_waitcnt lgkmcnt(0)
	v_mfma_f32_16x16x32_bf16 v[64:67], v[144:147], v[176:179], v[64:67]
	v_mfma_f32_16x16x32_bf16 v[64:67], v[148:151], v[180:183], v[64:67]
	v_mfma_f32_16x16x32_bf16 v[60:63], v[152:155], v[176:179], v[60:63]
	v_mfma_f32_16x16x32_bf16 v[60:63], v[156:159], v[180:183], v[60:63]
	v_mfma_f32_16x16x32_bf16 v[48:51], v[144:147], v[184:187], v[48:51]
	v_mfma_f32_16x16x32_bf16 v[48:51], v[148:151], v[188:191], v[48:51]
	v_mfma_f32_16x16x32_bf16 v[44:47], v[152:155], v[184:187], v[44:47]
	v_mfma_f32_16x16x32_bf16 v[44:47], v[156:159], v[188:191], v[44:47]
	v_mfma_f32_16x16x32_bf16 v[32:35], v[144:147], v[192:195], v[32:35]
	v_mfma_f32_16x16x32_bf16 v[32:35], v[148:151], v[196:199], v[32:35]
	v_mfma_f32_16x16x32_bf16 v[28:31], v[152:155], v[192:195], v[28:31]
	v_mfma_f32_16x16x32_bf16 v[28:31], v[156:159], v[196:199], v[28:31]
	v_mfma_f32_16x16x32_bf16 v[16:19], v[144:147], v[200:203], v[16:19]
	v_mfma_f32_16x16x32_bf16 v[16:19], v[148:151], v[204:207], v[16:19]
	v_mfma_f32_16x16x32_bf16 v[12:15], v[152:155], v[200:203], v[12:15]
	v_mfma_f32_16x16x32_bf16 v[12:15], v[156:159], v[204:207], v[12:15]
	s_setprio 0
	s_setprio 1
	v_mfma_f32_16x16x32_bf16 v[56:59], v[160:163], v[176:179], v[56:59]
	v_mfma_f32_16x16x32_bf16 v[56:59], v[164:167], v[180:183], v[56:59]
	v_mfma_f32_16x16x32_bf16 v[52:55], v[168:171], v[176:179], v[52:55]
	v_mfma_f32_16x16x32_bf16 v[52:55], v[172:175], v[180:183], v[52:55]
	v_mfma_f32_16x16x32_bf16 v[40:43], v[160:163], v[184:187], v[40:43]
	v_mfma_f32_16x16x32_bf16 v[40:43], v[164:167], v[188:191], v[40:43]
	v_mfma_f32_16x16x32_bf16 v[36:39], v[168:171], v[184:187], v[36:39]
	v_mfma_f32_16x16x32_bf16 v[36:39], v[172:175], v[188:191], v[36:39]
	v_mfma_f32_16x16x32_bf16 v[24:27], v[160:163], v[192:195], v[24:27]
	v_mfma_f32_16x16x32_bf16 v[24:27], v[164:167], v[196:199], v[24:27]
	v_mfma_f32_16x16x32_bf16 v[20:23], v[168:171], v[192:195], v[20:23]
	v_mfma_f32_16x16x32_bf16 v[20:23], v[172:175], v[196:199], v[20:23]
	v_mfma_f32_16x16x32_bf16 v[8:11], v[160:163], v[200:203], v[8:11]
	v_mfma_f32_16x16x32_bf16 v[8:11], v[164:167], v[204:207], v[8:11]
	v_mfma_f32_16x16x32_bf16 v[4:7], v[168:171], v[200:203], v[4:7]
	v_mfma_f32_16x16x32_bf16 v[4:7], v[172:175], v[204:207], v[4:7]
	s_setprio 0
	s_barrier
	v_add_u32_e32 v156, s45, v142
	v_add_u32_e32 v172, s74, v142
	ds_read_b128 v[144:147], v156
	ds_read_b128 v[148:151], v156 offset:1024
	ds_read_b128 v[152:155], v156 offset:2048
	ds_read_b128 v[156:159], v156 offset:3072
	ds_read_b128 v[160:163], v172
	ds_read_b128 v[164:167], v172 offset:1024
	ds_read_b128 v[168:171], v172 offset:2048
	ds_read_b128 v[172:175], v172 offset:3072
	s_add_u32 s10, s10, 0x80000
	s_addc_u32 s11, s11, 0
	s_mov_b32 m0, s22
	v_lshl_add_u64 v[220:221], s[10:11], 0, v[132:133]
	ds_read_b128 v[176:179], v143 offset:32768
	ds_read_b128 v[180:183], v143 offset:33792
	ds_read_b128 v[184:187], v143 offset:34816
	ds_read_b128 v[188:191], v143 offset:35840
	ds_read_b128 v[192:195], v143 offset:36864
	ds_read_b128 v[196:199], v143 offset:37888
	ds_read_b128 v[200:203], v143 offset:38912
	ds_read_b128 v[204:207], v143 offset:39936
	global_load_lds_dwordx4 v[220:221], off
	v_lshl_add_u64 v[220:221], s[10:11], 0, v[134:135]
	s_mov_b32 m0, s23
	s_nop 0
	global_load_lds_dwordx4 v[220:221], off
	s_waitcnt vmcnt(8)
	s_waitcnt lgkmcnt(0)
	s_barrier
	s_setprio 1
	s_waitcnt lgkmcnt(0)
	v_mfma_f32_16x16x32_bf16 v[128:131], v[144:147], v[176:179], v[128:131]
	v_mfma_f32_16x16x32_bf16 v[128:131], v[148:151], v[180:183], v[128:131]
	v_mfma_f32_16x16x32_bf16 v[124:127], v[152:155], v[176:179], v[124:127]
	v_mfma_f32_16x16x32_bf16 v[124:127], v[156:159], v[180:183], v[124:127]
	v_mfma_f32_16x16x32_bf16 v[112:115], v[144:147], v[184:187], v[112:115]
	v_mfma_f32_16x16x32_bf16 v[112:115], v[148:151], v[188:191], v[112:115]
	v_mfma_f32_16x16x32_bf16 v[108:111], v[152:155], v[184:187], v[108:111]
	v_mfma_f32_16x16x32_bf16 v[108:111], v[156:159], v[188:191], v[108:111]
	v_mfma_f32_16x16x32_bf16 v[96:99], v[144:147], v[192:195], v[96:99]
	v_mfma_f32_16x16x32_bf16 v[96:99], v[148:151], v[196:199], v[96:99]
	v_mfma_f32_16x16x32_bf16 v[92:95], v[152:155], v[192:195], v[92:95]
	v_mfma_f32_16x16x32_bf16 v[92:95], v[156:159], v[196:199], v[92:95]
	v_mfma_f32_16x16x32_bf16 v[80:83], v[144:147], v[200:203], v[80:83]
	v_mfma_f32_16x16x32_bf16 v[80:83], v[148:151], v[204:207], v[80:83]
	v_mfma_f32_16x16x32_bf16 v[76:79], v[152:155], v[200:203], v[76:79]
	v_mfma_f32_16x16x32_bf16 v[76:79], v[156:159], v[204:207], v[76:79]
	s_setprio 0
	s_setprio 1
	v_mfma_f32_16x16x32_bf16 v[120:123], v[160:163], v[176:179], v[120:123]
	v_mfma_f32_16x16x32_bf16 v[120:123], v[164:167], v[180:183], v[120:123]
	v_mfma_f32_16x16x32_bf16 v[116:119], v[168:171], v[176:179], v[116:119]
	v_mfma_f32_16x16x32_bf16 v[116:119], v[172:175], v[180:183], v[116:119]
	v_mfma_f32_16x16x32_bf16 v[104:107], v[160:163], v[184:187], v[104:107]
	v_mfma_f32_16x16x32_bf16 v[104:107], v[164:167], v[188:191], v[104:107]
	v_mfma_f32_16x16x32_bf16 v[100:103], v[168:171], v[184:187], v[100:103]
	v_mfma_f32_16x16x32_bf16 v[100:103], v[172:175], v[188:191], v[100:103]
	v_mfma_f32_16x16x32_bf16 v[88:91], v[160:163], v[192:195], v[88:91]
	v_mfma_f32_16x16x32_bf16 v[88:91], v[164:167], v[196:199], v[88:91]
	v_mfma_f32_16x16x32_bf16 v[84:87], v[168:171], v[192:195], v[84:87]
	v_mfma_f32_16x16x32_bf16 v[84:87], v[172:175], v[196:199], v[84:87]
	v_mfma_f32_16x16x32_bf16 v[72:75], v[160:163], v[200:203], v[72:75]
	v_mfma_f32_16x16x32_bf16 v[72:75], v[164:167], v[204:207], v[72:75]
	v_mfma_f32_16x16x32_bf16 v[68:71], v[168:171], v[200:203], v[68:71]
	v_mfma_f32_16x16x32_bf16 v[68:71], v[172:175], v[204:207], v[68:71]
	s_setprio 0
	s_barrier
	s_mov_b32 m0, s24
	v_lshl_add_u64 v[208:209], v[208:209], 0, s[64:65]
	s_add_u32 s8, s8, 0x80080
	ds_read_b128 v[176:179], v143 offset:49152
	ds_read_b128 v[180:183], v143 offset:50176
	ds_read_b128 v[184:187], v143 offset:51200
	ds_read_b128 v[188:191], v143 offset:52224
	ds_read_b128 v[192:195], v143 offset:53248
	ds_read_b128 v[196:199], v143 offset:54272
	ds_read_b128 v[200:203], v143 offset:55296
	ds_read_b128 v[204:207], v143 offset:56320
	global_load_lds_dwordx4 v[208:209], off
	v_lshl_add_u64 v[208:209], v[210:211], 0, s[64:65]
	s_mov_b32 m0, s25
	s_addc_u32 s9, s9, 0
	global_load_lds_dwordx4 v[208:209], off
	v_lshl_add_u64 v[208:209], s[8:9], 0, v[2:3]
	s_mov_b32 m0, s34
	s_nop 0
	global_load_lds_dwordx4 v[208:209], off
	v_lshl_add_u64 v[208:209], s[8:9], 0, v[136:137]
	s_mov_b32 m0, s35
	s_nop 0
	global_load_lds_dwordx4 v[208:209], off
	v_lshl_add_u64 v[208:209], v[216:217], 0, s[64:65]
	s_mov_b32 m0, s26
	s_nop 0
	global_load_lds_dwordx4 v[208:209], off
	v_lshl_add_u64 v[208:209], v[218:219], 0, s[64:65]
	s_mov_b32 m0, s27
	s_nop 0
	global_load_lds_dwordx4 v[208:209], off
	s_waitcnt vmcnt(8)
	s_waitcnt lgkmcnt(0)
	s_barrier
	s_setprio 1
	s_waitcnt lgkmcnt(0)
	v_mfma_f32_16x16x32_bf16 v[64:67], v[144:147], v[176:179], v[64:67]
	v_mfma_f32_16x16x32_bf16 v[64:67], v[148:151], v[180:183], v[64:67]
	v_mfma_f32_16x16x32_bf16 v[60:63], v[152:155], v[176:179], v[60:63]
	v_mfma_f32_16x16x32_bf16 v[60:63], v[156:159], v[180:183], v[60:63]
	v_mfma_f32_16x16x32_bf16 v[48:51], v[144:147], v[184:187], v[48:51]
	v_mfma_f32_16x16x32_bf16 v[48:51], v[148:151], v[188:191], v[48:51]
	v_mfma_f32_16x16x32_bf16 v[44:47], v[152:155], v[184:187], v[44:47]
	v_mfma_f32_16x16x32_bf16 v[44:47], v[156:159], v[188:191], v[44:47]
	v_mfma_f32_16x16x32_bf16 v[32:35], v[144:147], v[192:195], v[32:35]
	v_mfma_f32_16x16x32_bf16 v[32:35], v[148:151], v[196:199], v[32:35]
	v_mfma_f32_16x16x32_bf16 v[28:31], v[152:155], v[192:195], v[28:31]
	v_mfma_f32_16x16x32_bf16 v[28:31], v[156:159], v[196:199], v[28:31]
	v_mfma_f32_16x16x32_bf16 v[16:19], v[144:147], v[200:203], v[16:19]
	v_mfma_f32_16x16x32_bf16 v[16:19], v[148:151], v[204:207], v[16:19]
	v_mfma_f32_16x16x32_bf16 v[12:15], v[152:155], v[200:203], v[12:15]
	v_mfma_f32_16x16x32_bf16 v[12:15], v[156:159], v[204:207], v[12:15]
	s_setprio 0
	s_setprio 1
	v_mfma_f32_16x16x32_bf16 v[56:59], v[160:163], v[176:179], v[56:59]
	v_mfma_f32_16x16x32_bf16 v[56:59], v[164:167], v[180:183], v[56:59]
	v_mfma_f32_16x16x32_bf16 v[52:55], v[168:171], v[176:179], v[52:55]
	v_mfma_f32_16x16x32_bf16 v[52:55], v[172:175], v[180:183], v[52:55]
	v_mfma_f32_16x16x32_bf16 v[40:43], v[160:163], v[184:187], v[40:43]
	v_mfma_f32_16x16x32_bf16 v[40:43], v[164:167], v[188:191], v[40:43]
	v_mfma_f32_16x16x32_bf16 v[36:39], v[168:171], v[184:187], v[36:39]
	v_mfma_f32_16x16x32_bf16 v[36:39], v[172:175], v[188:191], v[36:39]
	v_mfma_f32_16x16x32_bf16 v[24:27], v[160:163], v[192:195], v[24:27]
	v_mfma_f32_16x16x32_bf16 v[24:27], v[164:167], v[196:199], v[24:27]
	v_mfma_f32_16x16x32_bf16 v[20:23], v[168:171], v[192:195], v[20:23]
	v_mfma_f32_16x16x32_bf16 v[20:23], v[172:175], v[196:199], v[20:23]
	v_mfma_f32_16x16x32_bf16 v[8:11], v[160:163], v[200:203], v[8:11]
	v_mfma_f32_16x16x32_bf16 v[8:11], v[164:167], v[204:207], v[8:11]
	v_mfma_f32_16x16x32_bf16 v[4:7], v[168:171], v[200:203], v[4:7]
	v_mfma_f32_16x16x32_bf16 v[4:7], v[172:175], v[204:207], v[4:7]
	s_setprio 0
	s_barrier
	s_add_i32 s43, s43, 2
	s_add_u32 s6, s6, 0x100
	s_addc_u32 s7, s7, 0
	s_cmp_gt_u32 s43, 29
	s_cbranch_scc0 .LBB0_1516
	s_cmpk_lt_u32 s21, 0x100
	s_cbranch_scc0 .LBB0_1519
	s_barrier

.LBB0_1876:
	v_add_u32_e32 v2, s83, v144
	ds_read_b128 v[146:149], v2
	ds_read_b128 v[150:153], v2 offset:1024
	ds_read_b128 v[154:157], v2 offset:2048
	ds_read_b128 v[158:161], v2 offset:3072
	v_add_u32_e32 v2, s44, v144
	ds_read_b128 v[162:165], v2
	ds_read_b128 v[166:169], v2 offset:1024
	ds_read_b128 v[170:173], v2 offset:2048
	ds_read_b128 v[174:177], v2 offset:3072
	s_add_i32 s70, s18, 2
	s_add_u32 s71, s42, 0x80
	s_addc_u32 s19, s43, 0
	s_cmp_eq_u32 s57, s18
	s_cselect_b32 s18, s34, s71
	s_cselect_b32 s19, s35, s19
	s_cselect_b32 s77, s25, s69
	s_cselect_b32 s76, s24, s68
	v_lshl_add_u64 v[210:211], s[42:43], 0, v[140:141]
	s_add_i32 m0, s23, 0xc000
	ds_read_b128 v[178:181], v145
	ds_read_b128 v[182:185], v145 offset:1024
	ds_read_b128 v[186:189], v145 offset:2048
	ds_read_b128 v[190:193], v145 offset:3072
	ds_read_b128 v[194:197], v145 offset:4096
	ds_read_b128 v[198:201], v145 offset:5120
	ds_read_b128 v[202:205], v145 offset:6144
	ds_read_b128 v[206:209], v145 offset:7168
	global_load_lds_dwordx4 v[210:211], off
	v_lshl_add_u64 v[210:211], s[42:43], 0, v[142:143]
	s_add_i32 m0, s23, 0xe000
	s_nop 0
	global_load_lds_dwordx4 v[210:211], off
	s_waitcnt vmcnt(8)
	s_waitcnt lgkmcnt(0)
	s_barrier
	s_setprio 1
	s_waitcnt lgkmcnt(0)
	v_mfma_f32_16x16x32_bf16 v[120:123], v[146:149], v[178:181], v[120:123]
	v_mfma_f32_16x16x32_bf16 v[120:123], v[150:153], v[182:185], v[120:123]
	v_mfma_f32_16x16x32_bf16 v[128:131], v[154:157], v[178:181], v[128:131]
	v_mfma_f32_16x16x32_bf16 v[128:131], v[158:161], v[182:185], v[128:131]
	v_mfma_f32_16x16x32_bf16 v[112:115], v[146:149], v[186:189], v[112:115]
	v_mfma_f32_16x16x32_bf16 v[112:115], v[150:153], v[190:193], v[112:115]
	v_mfma_f32_16x16x32_bf16 v[108:111], v[154:157], v[186:189], v[108:111]
	v_mfma_f32_16x16x32_bf16 v[108:111], v[158:161], v[190:193], v[108:111]
	v_mfma_f32_16x16x32_bf16 v[96:99], v[146:149], v[194:197], v[96:99]
	v_mfma_f32_16x16x32_bf16 v[96:99], v[150:153], v[198:201], v[96:99]
	v_mfma_f32_16x16x32_bf16 v[92:95], v[154:157], v[194:197], v[92:95]
	v_mfma_f32_16x16x32_bf16 v[92:95], v[158:161], v[198:201], v[92:95]
	v_mfma_f32_16x16x32_bf16 v[80:83], v[146:149], v[202:205], v[80:83]
	v_mfma_f32_16x16x32_bf16 v[80:83], v[150:153], v[206:209], v[80:83]
	v_mfma_f32_16x16x32_bf16 v[76:79], v[154:157], v[202:205], v[76:79]
	v_mfma_f32_16x16x32_bf16 v[76:79], v[158:161], v[206:209], v[76:79]
	s_setprio 0
	s_setprio 1
	v_mfma_f32_16x16x32_bf16 v[124:127], v[162:165], v[178:181], v[124:127]
	v_mfma_f32_16x16x32_bf16 v[124:127], v[166:169], v[182:185], v[124:127]
	v_mfma_f32_16x16x32_bf16 v[116:119], v[170:173], v[178:181], v[116:119]
	v_mfma_f32_16x16x32_bf16 v[116:119], v[174:177], v[182:185], v[116:119]
	v_mfma_f32_16x16x32_bf16 v[104:107], v[162:165], v[186:189], v[104:107]
	v_mfma_f32_16x16x32_bf16 v[104:107], v[166:169], v[190:193], v[104:107]
	v_mfma_f32_16x16x32_bf16 v[100:103], v[170:173], v[186:189], v[100:103]
	v_mfma_f32_16x16x32_bf16 v[100:103], v[174:177], v[190:193], v[100:103]
	v_mfma_f32_16x16x32_bf16 v[88:91], v[162:165], v[194:197], v[88:91]
	v_mfma_f32_16x16x32_bf16 v[88:91], v[166:169], v[198:201], v[88:91]
	v_mfma_f32_16x16x32_bf16 v[84:87], v[170:173], v[194:197], v[84:87]
	v_mfma_f32_16x16x32_bf16 v[84:87], v[174:177], v[198:201], v[84:87]
	v_mfma_f32_16x16x32_bf16 v[72:75], v[162:165], v[202:205], v[72:75]
	v_mfma_f32_16x16x32_bf16 v[72:75], v[166:169], v[206:209], v[72:75]
	v_mfma_f32_16x16x32_bf16 v[68:71], v[170:173], v[202:205], v[68:71]
	v_mfma_f32_16x16x32_bf16 v[68:71], v[174:177], v[206:209], v[68:71]
	s_setprio 0
	s_barrier
	s_mov_b32 m0, s16
	v_lshl_add_u64 v[210:211], s[76:77], 0, v[134:135]
	v_lshl_add_u64 v[216:217], s[76:77], 0, v[138:139]
	s_add_u32 s76, s76, s4
	ds_read_b128 v[178:181], v145 offset:16384
	ds_read_b128 v[182:185], v145 offset:17408
	ds_read_b128 v[186:189], v145 offset:18432
	ds_read_b128 v[190:193], v145 offset:19456
	ds_read_b128 v[194:197], v145 offset:20480
	ds_read_b128 v[198:201], v145 offset:21504
	ds_read_b128 v[202:205], v145 offset:22528
	ds_read_b128 v[206:209], v145 offset:23552
	global_load_lds_dwordx4 v[210:211], off
	s_mov_b32 m0, s20
	s_addc_u32 s77, s77, s5
	global_load_lds_dwordx4 v[216:217], off
	v_lshl_add_u64 v[218:219], s[76:77], 0, v[134:135]
	s_mov_b32 m0, s21
	v_lshl_add_u64 v[220:221], s[76:77], 0, v[138:139]
	global_load_lds_dwordx4 v[218:219], off
	s_mov_b32 m0, s22
	v_lshl_add_u64 v[222:223], s[18:19], 0, v[132:133]
	global_load_lds_dwordx4 v[220:221], off
	s_mov_b32 m0, s23
	v_lshl_add_u64 v[224:225], s[18:19], 0, v[136:137]
	global_load_lds_dwordx4 v[222:223], off
	s_mov_b32 m0, s26
	s_nop 0
	global_load_lds_dwordx4 v[224:225], off
	s_waitcnt vmcnt(8)
	s_waitcnt lgkmcnt(0)
	s_barrier
	s_setprio 1
	s_waitcnt lgkmcnt(0)
	v_mfma_f32_16x16x32_bf16 v[64:67], v[146:149], v[178:181], v[64:67]
	v_mfma_f32_16x16x32_bf16 v[64:67], v[150:153], v[182:185], v[64:67]
	v_mfma_f32_16x16x32_bf16 v[60:63], v[154:157], v[178:181], v[60:63]
	v_mfma_f32_16x16x32_bf16 v[60:63], v[158:161], v[182:185], v[60:63]
	v_mfma_f32_16x16x32_bf16 v[48:51], v[146:149], v[186:189], v[48:51]
	v_mfma_f32_16x16x32_bf16 v[48:51], v[150:153], v[190:193], v[48:51]
	v_mfma_f32_16x16x32_bf16 v[44:47], v[154:157], v[186:189], v[44:47]
	v_mfma_f32_16x16x32_bf16 v[44:47], v[158:161], v[190:193], v[44:47]
	v_mfma_f32_16x16x32_bf16 v[32:35], v[146:149], v[194:197], v[32:35]
	v_mfma_f32_16x16x32_bf16 v[32:35], v[150:153], v[198:201], v[32:35]
	v_mfma_f32_16x16x32_bf16 v[28:31], v[154:157], v[194:197], v[28:31]
	v_mfma_f32_16x16x32_bf16 v[28:31], v[158:161], v[198:201], v[28:31]
	v_mfma_f32_16x16x32_bf16 v[16:19], v[146:149], v[202:205], v[16:19]
	v_mfma_f32_16x16x32_bf16 v[16:19], v[150:153], v[206:209], v[16:19]
	v_mfma_f32_16x16x32_bf16 v[12:15], v[154:157], v[202:205], v[12:15]
	v_mfma_f32_16x16x32_bf16 v[12:15], v[158:161], v[206:209], v[12:15]
	s_setprio 0
	s_setprio 1
	v_mfma_f32_16x16x32_bf16 v[56:59], v[162:165], v[178:181], v[56:59]
	v_mfma_f32_16x16x32_bf16 v[56:59], v[166:169], v[182:185], v[56:59]
	v_mfma_f32_16x16x32_bf16 v[52:55], v[170:173], v[178:181], v[52:55]
	v_mfma_f32_16x16x32_bf16 v[52:55], v[174:177], v[182:185], v[52:55]
	v_mfma_f32_16x16x32_bf16 v[40:43], v[162:165], v[186:189], v[40:43]
	v_mfma_f32_16x16x32_bf16 v[40:43], v[166:169], v[190:193], v[40:43]
	v_mfma_f32_16x16x32_bf16 v[36:39], v[170:173], v[186:189], v[36:39]
	v_mfma_f32_16x16x32_bf16 v[36:39], v[174:177], v[190:193], v[36:39]
	v_mfma_f32_16x16x32_bf16 v[24:27], v[162:165], v[194:197], v[24:27]
	v_mfma_f32_16x16x32_bf16 v[24:27], v[166:169], v[198:201], v[24:27]
	v_mfma_f32_16x16x32_bf16 v[20:23], v[170:173], v[194:197], v[20:23]
	v_mfma_f32_16x16x32_bf16 v[20:23], v[174:177], v[198:201], v[20:23]
	v_mfma_f32_16x16x32_bf16 v[8:11], v[162:165], v[202:205], v[8:11]
	v_mfma_f32_16x16x32_bf16 v[8:11], v[166:169], v[206:209], v[8:11]
	v_mfma_f32_16x16x32_bf16 v[4:7], v[170:173], v[202:205], v[4:7]
	v_mfma_f32_16x16x32_bf16 v[4:7], v[174:177], v[206:209], v[4:7]
	s_setprio 0
	s_barrier
	v_add_u32_e32 v2, s45, v144
	ds_read_b128 v[146:149], v2
	ds_read_b128 v[150:153], v2 offset:1024
	ds_read_b128 v[154:157], v2 offset:2048
	ds_read_b128 v[158:161], v2 offset:3072
	v_add_u32_e32 v2, s74, v144
	ds_read_b128 v[162:165], v2
	ds_read_b128 v[166:169], v2 offset:1024
	ds_read_b128 v[170:173], v2 offset:2048
	ds_read_b128 v[174:177], v2 offset:3072
	s_add_u32 s18, s18, s4
	s_addc_u32 s19, s19, s5
	s_mov_b32 m0, s27
	v_lshl_add_u64 v[226:227], s[18:19], 0, v[132:133]
	ds_read_b128 v[178:181], v145 offset:32768
	ds_read_b128 v[182:185], v145 offset:33792
	ds_read_b128 v[186:189], v145 offset:34816
	ds_read_b128 v[190:193], v145 offset:35840
	ds_read_b128 v[194:197], v145 offset:36864
	ds_read_b128 v[198:201], v145 offset:37888
	ds_read_b128 v[202:205], v145 offset:38912
	ds_read_b128 v[206:209], v145 offset:39936
	global_load_lds_dwordx4 v[226:227], off
	v_lshl_add_u64 v[226:227], s[18:19], 0, v[136:137]
	s_mov_b32 m0, s37
	s_nop 0
	global_load_lds_dwordx4 v[226:227], off
	s_waitcnt vmcnt(8)
	s_waitcnt lgkmcnt(0)
	s_barrier
	s_setprio 1
	s_waitcnt lgkmcnt(0)
	v_mfma_f32_16x16x32_bf16 v[120:123], v[146:149], v[178:181], v[120:123]
	v_mfma_f32_16x16x32_bf16 v[120:123], v[150:153], v[182:185], v[120:123]
	v_mfma_f32_16x16x32_bf16 v[128:131], v[154:157], v[178:181], v[128:131]
	v_mfma_f32_16x16x32_bf16 v[128:131], v[158:161], v[182:185], v[128:131]
	v_mfma_f32_16x16x32_bf16 v[112:115], v[146:149], v[186:189], v[112:115]
	v_mfma_f32_16x16x32_bf16 v[112:115], v[150:153], v[190:193], v[112:115]
	v_mfma_f32_16x16x32_bf16 v[108:111], v[154:157], v[186:189], v[108:111]
	v_mfma_f32_16x16x32_bf16 v[108:111], v[158:161], v[190:193], v[108:111]
	v_mfma_f32_16x16x32_bf16 v[96:99], v[146:149], v[194:197], v[96:99]
	v_mfma_f32_16x16x32_bf16 v[96:99], v[150:153], v[198:201], v[96:99]
	v_mfma_f32_16x16x32_bf16 v[92:95], v[154:157], v[194:197], v[92:95]
	v_mfma_f32_16x16x32_bf16 v[92:95], v[158:161], v[198:201], v[92:95]
	v_mfma_f32_16x16x32_bf16 v[80:83], v[146:149], v[202:205], v[80:83]
	v_mfma_f32_16x16x32_bf16 v[80:83], v[150:153], v[206:209], v[80:83]
	v_mfma_f32_16x16x32_bf16 v[76:79], v[154:157], v[202:205], v[76:79]
	v_mfma_f32_16x16x32_bf16 v[76:79], v[158:161], v[206:209], v[76:79]
	s_setprio 0
	s_setprio 1
	v_mfma_f32_16x16x32_bf16 v[124:127], v[162:165], v[178:181], v[124:127]
	v_mfma_f32_16x16x32_bf16 v[124:127], v[166:169], v[182:185], v[124:127]
	v_mfma_f32_16x16x32_bf16 v[116:119], v[170:173], v[178:181], v[116:119]
	v_mfma_f32_16x16x32_bf16 v[116:119], v[174:177], v[182:185], v[116:119]
	v_mfma_f32_16x16x32_bf16 v[104:107], v[162:165], v[186:189], v[104:107]
	v_mfma_f32_16x16x32_bf16 v[104:107], v[166:169], v[190:193], v[104:107]
	v_mfma_f32_16x16x32_bf16 v[100:103], v[170:173], v[186:189], v[100:103]
	v_mfma_f32_16x16x32_bf16 v[100:103], v[174:177], v[190:193], v[100:103]
	v_mfma_f32_16x16x32_bf16 v[88:91], v[162:165], v[194:197], v[88:91]
	v_mfma_f32_16x16x32_bf16 v[88:91], v[166:169], v[198:201], v[88:91]
	v_mfma_f32_16x16x32_bf16 v[84:87], v[170:173], v[194:197], v[84:87]
	v_mfma_f32_16x16x32_bf16 v[84:87], v[174:177], v[198:201], v[84:87]
	v_mfma_f32_16x16x32_bf16 v[72:75], v[162:165], v[202:205], v[72:75]
	v_mfma_f32_16x16x32_bf16 v[72:75], v[166:169], v[206:209], v[72:75]
	v_mfma_f32_16x16x32_bf16 v[68:71], v[170:173], v[202:205], v[68:71]
	v_mfma_f32_16x16x32_bf16 v[68:71], v[174:177], v[206:209], v[68:71]
	s_setprio 0
	s_barrier
	s_mov_b32 m0, s49
	v_lshl_add_u64 v[210:211], v[210:211], 0, s[64:65]
	ds_read_b128 v[178:181], v145 offset:49152
	ds_read_b128 v[182:185], v145 offset:50176
	ds_read_b128 v[186:189], v145 offset:51200
	ds_read_b128 v[190:193], v145 offset:52224
	ds_read_b128 v[194:197], v145 offset:53248
	ds_read_b128 v[198:201], v145 offset:54272
	ds_read_b128 v[202:205], v145 offset:55296
	ds_read_b128 v[206:209], v145 offset:56320
	global_load_lds_dwordx4 v[210:211], off
	v_lshl_add_u64 v[210:211], v[216:217], 0, s[64:65]
	s_mov_b32 m0, s50
	s_nop 0
	global_load_lds_dwordx4 v[210:211], off
	v_lshl_add_u64 v[210:211], v[218:219], 0, s[64:65]
	s_mov_b32 m0, s53
	s_nop 0
	global_load_lds_dwordx4 v[210:211], off
	v_lshl_add_u64 v[210:211], v[220:221], 0, s[64:65]
	s_mov_b32 m0, s56
	s_nop 0
	global_load_lds_dwordx4 v[210:211], off
	v_lshl_add_u64 v[210:211], v[222:223], 0, s[64:65]
	s_mov_b32 m0, s51
	s_nop 0
	global_load_lds_dwordx4 v[210:211], off
	v_lshl_add_u64 v[210:211], v[224:225], 0, s[64:65]
	s_mov_b32 m0, s52
	s_nop 0
	global_load_lds_dwordx4 v[210:211], off
	s_waitcnt vmcnt(8)
	s_waitcnt lgkmcnt(0)
	s_barrier
	s_setprio 1
	s_waitcnt lgkmcnt(0)
	v_mfma_f32_16x16x32_bf16 v[64:67], v[146:149], v[178:181], v[64:67]
	v_mfma_f32_16x16x32_bf16 v[64:67], v[150:153], v[182:185], v[64:67]
	v_mfma_f32_16x16x32_bf16 v[60:63], v[154:157], v[178:181], v[60:63]
	v_mfma_f32_16x16x32_bf16 v[60:63], v[158:161], v[182:185], v[60:63]
	v_mfma_f32_16x16x32_bf16 v[48:51], v[146:149], v[186:189], v[48:51]
	v_mfma_f32_16x16x32_bf16 v[48:51], v[150:153], v[190:193], v[48:51]
	v_mfma_f32_16x16x32_bf16 v[44:47], v[154:157], v[186:189], v[44:47]
	v_mfma_f32_16x16x32_bf16 v[44:47], v[158:161], v[190:193], v[44:47]
	v_mfma_f32_16x16x32_bf16 v[32:35], v[146:149], v[194:197], v[32:35]
	v_mfma_f32_16x16x32_bf16 v[32:35], v[150:153], v[198:201], v[32:35]
	v_mfma_f32_16x16x32_bf16 v[28:31], v[154:157], v[194:197], v[28:31]
	v_mfma_f32_16x16x32_bf16 v[28:31], v[158:161], v[198:201], v[28:31]
	v_mfma_f32_16x16x32_bf16 v[16:19], v[146:149], v[202:205], v[16:19]
	v_mfma_f32_16x16x32_bf16 v[16:19], v[150:153], v[206:209], v[16:19]
	v_mfma_f32_16x16x32_bf16 v[12:15], v[154:157], v[202:205], v[12:15]
	v_mfma_f32_16x16x32_bf16 v[12:15], v[158:161], v[206:209], v[12:15]
	s_setprio 0
	s_setprio 1
	v_mfma_f32_16x16x32_bf16 v[56:59], v[162:165], v[178:181], v[56:59]
	v_mfma_f32_16x16x32_bf16 v[56:59], v[166:169], v[182:185], v[56:59]
	v_mfma_f32_16x16x32_bf16 v[52:55], v[170:173], v[178:181], v[52:55]
	v_mfma_f32_16x16x32_bf16 v[52:55], v[174:177], v[182:185], v[52:55]
	v_mfma_f32_16x16x32_bf16 v[40:43], v[162:165], v[186:189], v[40:43]
	v_mfma_f32_16x16x32_bf16 v[40:43], v[166:169], v[190:193], v[40:43]
	v_mfma_f32_16x16x32_bf16 v[36:39], v[170:173], v[186:189], v[36:39]
	v_mfma_f32_16x16x32_bf16 v[36:39], v[174:177], v[190:193], v[36:39]
	v_mfma_f32_16x16x32_bf16 v[24:27], v[162:165], v[194:197], v[24:27]
	v_mfma_f32_16x16x32_bf16 v[24:27], v[166:169], v[198:201], v[24:27]
	v_mfma_f32_16x16x32_bf16 v[20:23], v[170:173], v[194:197], v[20:23]
	v_mfma_f32_16x16x32_bf16 v[20:23], v[174:177], v[198:201], v[20:23]
	v_mfma_f32_16x16x32_bf16 v[8:11], v[162:165], v[202:205], v[8:11]
	v_mfma_f32_16x16x32_bf16 v[8:11], v[166:169], v[206:209], v[8:11]
	v_mfma_f32_16x16x32_bf16 v[4:7], v[170:173], v[202:205], v[4:7]
	v_mfma_f32_16x16x32_bf16 v[4:7], v[174:177], v[206:209], v[4:7]
	s_setprio 0
	s_barrier
	s_add_u32 s42, s42, 0x100
	s_addc_u32 s43, s43, 0
	s_add_u32 s68, s68, 0x100
	s_addc_u32 s69, s69, 0
	s_cmp_ge_i32 s70, s46
	s_mov_b32 s18, s70
	s_cbranch_scc0 .LBB0_1876

.LBB0_2329:
	s_add_i32 s43, s12, 2
	v_add_u32_e32 v156, s83, v142
	v_add_u32_e32 v172, s44, v142
	s_add_u32 s10, s8, 0x100
	ds_read_b128 v[144:147], v156
	ds_read_b128 v[148:151], v156 offset:1024
	ds_read_b128 v[152:155], v156 offset:2048
	ds_read_b128 v[156:159], v156 offset:3072
	ds_read_b128 v[160:163], v172
	ds_read_b128 v[164:167], v172 offset:1024
	ds_read_b128 v[168:171], v172 offset:2048
	ds_read_b128 v[172:175], v172 offset:3072
	s_addc_u32 s11, s9, 0
	s_cmp_lg_u32 s42, s12
	s_cselect_b32 s46, s10, 0
	s_cselect_b32 s47, s11, 0
	s_add_u32 s12, s6, s46
	s_addc_u32 s13, s7, s47
	s_add_u32 s46, s4, s46
	s_addc_u32 s47, s5, s47
	v_lshl_add_u64 v[208:209], v[138:139], 0, s[8:9]
	s_add_i32 m0, s22, 0xc000
	ds_read_b128 v[176:179], v143
	ds_read_b128 v[180:183], v143 offset:1024
	ds_read_b128 v[184:187], v143 offset:2048
	ds_read_b128 v[188:191], v143 offset:3072
	ds_read_b128 v[192:195], v143 offset:4096
	ds_read_b128 v[196:199], v143 offset:5120
	ds_read_b128 v[200:203], v143 offset:6144
	ds_read_b128 v[204:207], v143 offset:7168
	global_load_lds_dwordx4 v[208:209], off
	v_lshl_add_u64 v[208:209], v[140:141], 0, s[8:9]
	s_add_i32 m0, s22, 0xe000
	s_nop 0
	global_load_lds_dwordx4 v[208:209], off
	s_waitcnt vmcnt(8)
	s_waitcnt lgkmcnt(0)
	s_barrier
	s_setprio 1
	s_waitcnt lgkmcnt(0)
	v_mfma_f32_16x16x32_bf16 v[124:127], v[144:147], v[176:179], v[124:127]
	v_mfma_f32_16x16x32_bf16 v[124:127], v[148:151], v[180:183], v[124:127]
	v_mfma_f32_16x16x32_bf16 v[128:131], v[152:155], v[176:179], v[128:131]
	v_mfma_f32_16x16x32_bf16 v[128:131], v[156:159], v[180:183], v[128:131]
	v_mfma_f32_16x16x32_bf16 v[112:115], v[144:147], v[184:187], v[112:115]
	v_mfma_f32_16x16x32_bf16 v[112:115], v[148:151], v[188:191], v[112:115]
	v_mfma_f32_16x16x32_bf16 v[108:111], v[152:155], v[184:187], v[108:111]
	v_mfma_f32_16x16x32_bf16 v[108:111], v[156:159], v[188:191], v[108:111]
	v_mfma_f32_16x16x32_bf16 v[96:99], v[144:147], v[192:195], v[96:99]
	v_mfma_f32_16x16x32_bf16 v[96:99], v[148:151], v[196:199], v[96:99]
	v_mfma_f32_16x16x32_bf16 v[92:95], v[152:155], v[192:195], v[92:95]
	v_mfma_f32_16x16x32_bf16 v[92:95], v[156:159], v[196:199], v[92:95]
	v_mfma_f32_16x16x32_bf16 v[80:83], v[144:147], v[200:203], v[80:83]
	v_mfma_f32_16x16x32_bf16 v[80:83], v[148:151], v[204:207], v[80:83]
	v_mfma_f32_16x16x32_bf16 v[76:79], v[152:155], v[200:203], v[76:79]
	v_mfma_f32_16x16x32_bf16 v[76:79], v[156:159], v[204:207], v[76:79]
	s_setprio 0
	s_setprio 1
	v_mfma_f32_16x16x32_bf16 v[120:123], v[160:163], v[176:179], v[120:123]
	v_mfma_f32_16x16x32_bf16 v[120:123], v[164:167], v[180:183], v[120:123]
	v_mfma_f32_16x16x32_bf16 v[116:119], v[168:171], v[176:179], v[116:119]
	v_mfma_f32_16x16x32_bf16 v[116:119], v[172:175], v[180:183], v[116:119]
	v_mfma_f32_16x16x32_bf16 v[104:107], v[160:163], v[184:187], v[104:107]
	v_mfma_f32_16x16x32_bf16 v[104:107], v[164:167], v[188:191], v[104:107]
	v_mfma_f32_16x16x32_bf16 v[100:103], v[168:171], v[184:187], v[100:103]
	v_mfma_f32_16x16x32_bf16 v[100:103], v[172:175], v[188:191], v[100:103]
	v_mfma_f32_16x16x32_bf16 v[88:91], v[160:163], v[192:195], v[88:91]
	v_mfma_f32_16x16x32_bf16 v[88:91], v[164:167], v[196:199], v[88:91]
	v_mfma_f32_16x16x32_bf16 v[84:87], v[168:171], v[192:195], v[84:87]
	v_mfma_f32_16x16x32_bf16 v[84:87], v[172:175], v[196:199], v[84:87]
	v_mfma_f32_16x16x32_bf16 v[72:75], v[160:163], v[200:203], v[72:75]
	v_mfma_f32_16x16x32_bf16 v[72:75], v[164:167], v[204:207], v[72:75]
	v_mfma_f32_16x16x32_bf16 v[68:71], v[168:171], v[200:203], v[68:71]
	v_mfma_f32_16x16x32_bf16 v[68:71], v[172:175], v[204:207], v[68:71]
	s_setprio 0
	s_barrier
	s_mov_b32 m0, s18
	v_lshl_add_u64 v[208:209], s[46:47], 0, v[2:3]
	s_add_u32 s8, s46, s2
	ds_read_b128 v[176:179], v143 offset:16384
	ds_read_b128 v[180:183], v143 offset:17408
	ds_read_b128 v[184:187], v143 offset:18432
	ds_read_b128 v[188:191], v143 offset:19456
	ds_read_b128 v[192:195], v143 offset:20480
	ds_read_b128 v[196:199], v143 offset:21504
	ds_read_b128 v[200:203], v143 offset:22528
	ds_read_b128 v[204:207], v143 offset:23552
	global_load_lds_dwordx4 v[208:209], off
	v_lshl_add_u64 v[210:211], s[46:47], 0, v[136:137]
	s_mov_b32 m0, s19
	s_addc_u32 s9, s47, s3
	global_load_lds_dwordx4 v[210:211], off
	v_lshl_add_u64 v[216:217], s[8:9], 0, v[2:3]
	s_mov_b32 m0, s20
	v_lshl_add_u64 v[218:219], s[8:9], 0, v[136:137]
	global_load_lds_dwordx4 v[216:217], off
	s_mov_b32 m0, s21
	v_lshl_add_u64 v[220:221], s[12:13], 0, v[132:133]
	global_load_lds_dwordx4 v[218:219], off
	s_mov_b32 m0, s22
	v_lshl_add_u64 v[222:223], s[12:13], 0, v[134:135]
	global_load_lds_dwordx4 v[220:221], off
	s_mov_b32 m0, s23
	s_nop 0
	global_load_lds_dwordx4 v[222:223], off
	s_waitcnt vmcnt(8)
	s_waitcnt lgkmcnt(0)
	s_barrier
	s_setprio 1
	s_waitcnt lgkmcnt(0)
	v_mfma_f32_16x16x32_bf16 v[64:67], v[144:147], v[176:179], v[64:67]
	v_mfma_f32_16x16x32_bf16 v[64:67], v[148:151], v[180:183], v[64:67]
	v_mfma_f32_16x16x32_bf16 v[60:63], v[152:155], v[176:179], v[60:63]
	v_mfma_f32_16x16x32_bf16 v[60:63], v[156:159], v[180:183], v[60:63]
	v_mfma_f32_16x16x32_bf16 v[48:51], v[144:147], v[184:187], v[48:51]
	v_mfma_f32_16x16x32_bf16 v[48:51], v[148:151], v[188:191], v[48:51]
	v_mfma_f32_16x16x32_bf16 v[44:47], v[152:155], v[184:187], v[44:47]
	v_mfma_f32_16x16x32_bf16 v[44:47], v[156:159], v[188:191], v[44:47]
	v_mfma_f32_16x16x32_bf16 v[32:35], v[144:147], v[192:195], v[32:35]
	v_mfma_f32_16x16x32_bf16 v[32:35], v[148:151], v[196:199], v[32:35]
	v_mfma_f32_16x16x32_bf16 v[28:31], v[152:155], v[192:195], v[28:31]
	v_mfma_f32_16x16x32_bf16 v[28:31], v[156:159], v[196:199], v[28:31]
	v_mfma_f32_16x16x32_bf16 v[16:19], v[144:147], v[200:203], v[16:19]
	v_mfma_f32_16x16x32_bf16 v[16:19], v[148:151], v[204:207], v[16:19]
	v_mfma_f32_16x16x32_bf16 v[12:15], v[152:155], v[200:203], v[12:15]
	v_mfma_f32_16x16x32_bf16 v[12:15], v[156:159], v[204:207], v[12:15]
	s_setprio 0
	s_setprio 1
	v_mfma_f32_16x16x32_bf16 v[56:59], v[160:163], v[176:179], v[56:59]
	v_mfma_f32_16x16x32_bf16 v[56:59], v[164:167], v[180:183], v[56:59]
	v_mfma_f32_16x16x32_bf16 v[52:55], v[168:171], v[176:179], v[52:55]
	v_mfma_f32_16x16x32_bf16 v[52:55], v[172:175], v[180:183], v[52:55]
	v_mfma_f32_16x16x32_bf16 v[40:43], v[160:163], v[184:187], v[40:43]
	v_mfma_f32_16x16x32_bf16 v[40:43], v[164:167], v[188:191], v[40:43]
	v_mfma_f32_16x16x32_bf16 v[36:39], v[168:171], v[184:187], v[36:39]
	v_mfma_f32_16x16x32_bf16 v[36:39], v[172:175], v[188:191], v[36:39]
	v_mfma_f32_16x16x32_bf16 v[24:27], v[160:163], v[192:195], v[24:27]
	v_mfma_f32_16x16x32_bf16 v[24:27], v[164:167], v[196:199], v[24:27]
	v_mfma_f32_16x16x32_bf16 v[20:23], v[168:171], v[192:195], v[20:23]
	v_mfma_f32_16x16x32_bf16 v[20:23], v[172:175], v[196:199], v[20:23]
	v_mfma_f32_16x16x32_bf16 v[8:11], v[160:163], v[200:203], v[8:11]
	v_mfma_f32_16x16x32_bf16 v[8:11], v[164:167], v[204:207], v[8:11]
	v_mfma_f32_16x16x32_bf16 v[4:7], v[168:171], v[200:203], v[4:7]
	v_mfma_f32_16x16x32_bf16 v[4:7], v[172:175], v[204:207], v[4:7]
	s_setprio 0
	s_barrier
	v_add_u32_e32 v156, s45, v142
	v_add_u32_e32 v172, s74, v142
	ds_read_b128 v[144:147], v156
	ds_read_b128 v[148:151], v156 offset:1024
	ds_read_b128 v[152:155], v156 offset:2048
	ds_read_b128 v[156:159], v156 offset:3072
	ds_read_b128 v[160:163], v172
	ds_read_b128 v[164:167], v172 offset:1024
	ds_read_b128 v[168:171], v172 offset:2048
	ds_read_b128 v[172:175], v172 offset:3072
	s_add_u32 s8, s12, s2
	s_addc_u32 s9, s13, s3
	s_mov_b32 m0, s24
	v_lshl_add_u64 v[224:225], s[8:9], 0, v[132:133]
	ds_read_b128 v[176:179], v143 offset:32768
	ds_read_b128 v[180:183], v143 offset:33792
	ds_read_b128 v[184:187], v143 offset:34816
	ds_read_b128 v[188:191], v143 offset:35840
	ds_read_b128 v[192:195], v143 offset:36864
	ds_read_b128 v[196:199], v143 offset:37888
	ds_read_b128 v[200:203], v143 offset:38912
	ds_read_b128 v[204:207], v143 offset:39936
	global_load_lds_dwordx4 v[224:225], off
	v_lshl_add_u64 v[224:225], s[8:9], 0, v[134:135]
	s_mov_b32 m0, s25
	s_nop 0
	global_load_lds_dwordx4 v[224:225], off
	s_waitcnt vmcnt(8)
	s_waitcnt lgkmcnt(0)
	s_barrier
	s_setprio 1
	s_waitcnt lgkmcnt(0)
	v_mfma_f32_16x16x32_bf16 v[124:127], v[144:147], v[176:179], v[124:127]
	v_mfma_f32_16x16x32_bf16 v[124:127], v[148:151], v[180:183], v[124:127]
	v_mfma_f32_16x16x32_bf16 v[128:131], v[152:155], v[176:179], v[128:131]
	v_mfma_f32_16x16x32_bf16 v[128:131], v[156:159], v[180:183], v[128:131]
	v_mfma_f32_16x16x32_bf16 v[112:115], v[144:147], v[184:187], v[112:115]
	v_mfma_f32_16x16x32_bf16 v[112:115], v[148:151], v[188:191], v[112:115]
	v_mfma_f32_16x16x32_bf16 v[108:111], v[152:155], v[184:187], v[108:111]
	v_mfma_f32_16x16x32_bf16 v[108:111], v[156:159], v[188:191], v[108:111]
	v_mfma_f32_16x16x32_bf16 v[96:99], v[144:147], v[192:195], v[96:99]
	v_mfma_f32_16x16x32_bf16 v[96:99], v[148:151], v[196:199], v[96:99]
	v_mfma_f32_16x16x32_bf16 v[92:95], v[152:155], v[192:195], v[92:95]
	v_mfma_f32_16x16x32_bf16 v[92:95], v[156:159], v[196:199], v[92:95]
	v_mfma_f32_16x16x32_bf16 v[80:83], v[144:147], v[200:203], v[80:83]
	v_mfma_f32_16x16x32_bf16 v[80:83], v[148:151], v[204:207], v[80:83]
	v_mfma_f32_16x16x32_bf16 v[76:79], v[152:155], v[200:203], v[76:79]
	v_mfma_f32_16x16x32_bf16 v[76:79], v[156:159], v[204:207], v[76:79]
	s_setprio 0
	s_setprio 1
	v_mfma_f32_16x16x32_bf16 v[120:123], v[160:163], v[176:179], v[120:123]
	v_mfma_f32_16x16x32_bf16 v[120:123], v[164:167], v[180:183], v[120:123]
	v_mfma_f32_16x16x32_bf16 v[116:119], v[168:171], v[176:179], v[116:119]
	v_mfma_f32_16x16x32_bf16 v[116:119], v[172:175], v[180:183], v[116:119]
	v_mfma_f32_16x16x32_bf16 v[104:107], v[160:163], v[184:187], v[104:107]
	v_mfma_f32_16x16x32_bf16 v[104:107], v[164:167], v[188:191], v[104:107]
	v_mfma_f32_16x16x32_bf16 v[100:103], v[168:171], v[184:187], v[100:103]
	v_mfma_f32_16x16x32_bf16 v[100:103], v[172:175], v[188:191], v[100:103]
	v_mfma_f32_16x16x32_bf16 v[88:91], v[160:163], v[192:195], v[88:91]
	v_mfma_f32_16x16x32_bf16 v[88:91], v[164:167], v[196:199], v[88:91]
	v_mfma_f32_16x16x32_bf16 v[84:87], v[168:171], v[192:195], v[84:87]
	v_mfma_f32_16x16x32_bf16 v[84:87], v[172:175], v[196:199], v[84:87]
	v_mfma_f32_16x16x32_bf16 v[72:75], v[160:163], v[200:203], v[72:75]
	v_mfma_f32_16x16x32_bf16 v[72:75], v[164:167], v[204:207], v[72:75]
	v_mfma_f32_16x16x32_bf16 v[68:71], v[168:171], v[200:203], v[68:71]
	v_mfma_f32_16x16x32_bf16 v[68:71], v[172:175], v[204:207], v[68:71]
	s_setprio 0
	s_barrier
	s_mov_b32 m0, s26
	v_lshl_add_u64 v[208:209], v[208:209], 0, s[64:65]
	ds_read_b128 v[176:179], v143 offset:49152
	ds_read_b128 v[180:183], v143 offset:50176
	ds_read_b128 v[184:187], v143 offset:51200
	ds_read_b128 v[188:191], v143 offset:52224
	ds_read_b128 v[192:195], v143 offset:53248
	ds_read_b128 v[196:199], v143 offset:54272
	ds_read_b128 v[200:203], v143 offset:55296
	ds_read_b128 v[204:207], v143 offset:56320
	global_load_lds_dwordx4 v[208:209], off
	v_lshl_add_u64 v[208:209], v[210:211], 0, s[64:65]
	s_mov_b32 m0, s27
	s_nop 0
	global_load_lds_dwordx4 v[208:209], off
	v_lshl_add_u64 v[208:209], v[216:217], 0, s[64:65]
	s_mov_b32 m0, s37
	s_nop 0
	global_load_lds_dwordx4 v[208:209], off
	v_lshl_add_u64 v[208:209], v[218:219], 0, s[64:65]
	s_mov_b32 m0, s40
	s_nop 0
	global_load_lds_dwordx4 v[208:209], off
	v_lshl_add_u64 v[208:209], v[220:221], 0, s[64:65]
	s_mov_b32 m0, s34
	s_nop 0
	global_load_lds_dwordx4 v[208:209], off
	v_lshl_add_u64 v[208:209], v[222:223], 0, s[64:65]
	s_mov_b32 m0, s35
	s_nop 0
	global_load_lds_dwordx4 v[208:209], off
	s_waitcnt vmcnt(8)
	s_waitcnt lgkmcnt(0)
	s_barrier
	s_setprio 1
	s_waitcnt lgkmcnt(0)
	v_mfma_f32_16x16x32_bf16 v[64:67], v[144:147], v[176:179], v[64:67]
	v_mfma_f32_16x16x32_bf16 v[64:67], v[148:151], v[180:183], v[64:67]
	v_mfma_f32_16x16x32_bf16 v[60:63], v[152:155], v[176:179], v[60:63]
	v_mfma_f32_16x16x32_bf16 v[60:63], v[156:159], v[180:183], v[60:63]
	v_mfma_f32_16x16x32_bf16 v[48:51], v[144:147], v[184:187], v[48:51]
	v_mfma_f32_16x16x32_bf16 v[48:51], v[148:151], v[188:191], v[48:51]
	v_mfma_f32_16x16x32_bf16 v[44:47], v[152:155], v[184:187], v[44:47]
	v_mfma_f32_16x16x32_bf16 v[44:47], v[156:159], v[188:191], v[44:47]
	v_mfma_f32_16x16x32_bf16 v[32:35], v[144:147], v[192:195], v[32:35]
	v_mfma_f32_16x16x32_bf16 v[32:35], v[148:151], v[196:199], v[32:35]
	v_mfma_f32_16x16x32_bf16 v[28:31], v[152:155], v[192:195], v[28:31]
	v_mfma_f32_16x16x32_bf16 v[28:31], v[156:159], v[196:199], v[28:31]
	v_mfma_f32_16x16x32_bf16 v[16:19], v[144:147], v[200:203], v[16:19]
	v_mfma_f32_16x16x32_bf16 v[16:19], v[148:151], v[204:207], v[16:19]
	v_mfma_f32_16x16x32_bf16 v[12:15], v[152:155], v[200:203], v[12:15]
	v_mfma_f32_16x16x32_bf16 v[12:15], v[156:159], v[204:207], v[12:15]
	s_setprio 0
	s_setprio 1
	v_mfma_f32_16x16x32_bf16 v[56:59], v[160:163], v[176:179], v[56:59]
	v_mfma_f32_16x16x32_bf16 v[56:59], v[164:167], v[180:183], v[56:59]
	v_mfma_f32_16x16x32_bf16 v[52:55], v[168:171], v[176:179], v[52:55]
	v_mfma_f32_16x16x32_bf16 v[52:55], v[172:175], v[180:183], v[52:55]
	v_mfma_f32_16x16x32_bf16 v[40:43], v[160:163], v[184:187], v[40:43]
	v_mfma_f32_16x16x32_bf16 v[40:43], v[164:167], v[188:191], v[40:43]
	v_mfma_f32_16x16x32_bf16 v[36:39], v[168:171], v[184:187], v[36:39]
	v_mfma_f32_16x16x32_bf16 v[36:39], v[172:175], v[188:191], v[36:39]
	v_mfma_f32_16x16x32_bf16 v[24:27], v[160:163], v[192:195], v[24:27]
	v_mfma_f32_16x16x32_bf16 v[24:27], v[164:167], v[196:199], v[24:27]
	v_mfma_f32_16x16x32_bf16 v[20:23], v[168:171], v[192:195], v[20:23]
	v_mfma_f32_16x16x32_bf16 v[20:23], v[172:175], v[196:199], v[20:23]
	v_mfma_f32_16x16x32_bf16 v[8:11], v[160:163], v[200:203], v[8:11]
	v_mfma_f32_16x16x32_bf16 v[8:11], v[164:167], v[204:207], v[8:11]
	v_mfma_f32_16x16x32_bf16 v[4:7], v[168:171], v[200:203], v[4:7]
	v_mfma_f32_16x16x32_bf16 v[4:7], v[172:175], v[204:207], v[4:7]
	s_setprio 0
	s_barrier
	s_cmp_ge_i32 s43, s41
	s_mov_b64 s[8:9], s[10:11]
	s_mov_b32 s12, s43
	s_cbranch_scc0 .LBB0_2329

.LBB0_2896:
	v_add_u32_e32 v148, s18, v126
	v_add_u32_e32 v172, s19, v126
	s_add_u32 s12, s46, s8
	ds_read_b128 v[128:131], v148
	ds_read_b128 v[132:135], v148 offset:1024
	ds_read_b128 v[140:143], v148 offset:2048
	ds_read_b128 v[148:151], v148 offset:3072
	ds_read_b128 v[160:163], v172
	ds_read_b128 v[164:167], v172 offset:1024
	ds_read_b128 v[168:171], v172 offset:2048
	ds_read_b128 v[172:175], v172 offset:3072
	s_addc_u32 s13, s47, s9
	s_add_u32 s12, s12, 0x34400100
	s_addc_u32 s13, s13, 0
	s_add_u32 s16, s48, s8
	s_addc_u32 s51, s49, s9
	s_cmpk_eq_i32 s8, 0xf00
	s_cselect_b32 s15, s11, s13
	s_cselect_b32 s14, s10, s12
	s_cselect_b32 s13, s3, s51
	s_cselect_b32 s12, s2, s16
	v_lshl_add_u64 v[208:209], v[122:123], 0, s[8:9]
	s_add_i32 m0, s27, 0xc000
	ds_read_b128 v[176:179], v127
	ds_read_b128 v[180:183], v127 offset:1024
	ds_read_b128 v[184:187], v127 offset:2048
	ds_read_b128 v[188:191], v127 offset:3072
	ds_read_b128 v[192:195], v127 offset:4096
	ds_read_b128 v[196:199], v127 offset:5120
	ds_read_b128 v[200:203], v127 offset:6144
	ds_read_b128 v[204:207], v127 offset:7168
	global_load_lds_dwordx4 v[208:209], off
	v_lshl_add_u64 v[208:209], v[124:125], 0, s[8:9]
	s_add_i32 m0, s27, 0xe000
	s_nop 0
	global_load_lds_dwordx4 v[208:209], off
	s_waitcnt vmcnt(8)
	s_waitcnt lgkmcnt(0)
	s_barrier
	s_setprio 1
	s_waitcnt lgkmcnt(0)
	v_mfma_f32_16x16x32_bf16 v[156:159], v[128:131], v[176:179], v[156:159]
	v_mfma_f32_16x16x32_bf16 v[156:159], v[132:135], v[180:183], v[156:159]
	v_mfma_f32_16x16x32_bf16 v[152:155], v[140:143], v[176:179], v[152:155]
	v_mfma_f32_16x16x32_bf16 v[152:155], v[148:151], v[180:183], v[152:155]
	v_mfma_f32_16x16x32_bf16 v[112:115], v[128:131], v[184:187], v[112:115]
	v_mfma_f32_16x16x32_bf16 v[112:115], v[132:135], v[188:191], v[112:115]
	v_mfma_f32_16x16x32_bf16 v[108:111], v[140:143], v[184:187], v[108:111]
	v_mfma_f32_16x16x32_bf16 v[108:111], v[148:151], v[188:191], v[108:111]
	v_mfma_f32_16x16x32_bf16 v[96:99], v[128:131], v[192:195], v[96:99]
	v_mfma_f32_16x16x32_bf16 v[96:99], v[132:135], v[196:199], v[96:99]
	v_mfma_f32_16x16x32_bf16 v[92:95], v[140:143], v[192:195], v[92:95]
	v_mfma_f32_16x16x32_bf16 v[92:95], v[148:151], v[196:199], v[92:95]
	v_mfma_f32_16x16x32_bf16 v[80:83], v[128:131], v[200:203], v[80:83]
	v_mfma_f32_16x16x32_bf16 v[80:83], v[132:135], v[204:207], v[80:83]
	v_mfma_f32_16x16x32_bf16 v[76:79], v[140:143], v[200:203], v[76:79]
	v_mfma_f32_16x16x32_bf16 v[76:79], v[148:151], v[204:207], v[76:79]
	s_setprio 0
	s_setprio 1
	v_mfma_f32_16x16x32_bf16 v[144:147], v[160:163], v[176:179], v[144:147]
	v_mfma_f32_16x16x32_bf16 v[144:147], v[164:167], v[180:183], v[144:147]
	v_mfma_f32_16x16x32_bf16 v[136:139], v[168:171], v[176:179], v[136:139]
	v_mfma_f32_16x16x32_bf16 v[136:139], v[172:175], v[180:183], v[136:139]
	v_mfma_f32_16x16x32_bf16 v[104:107], v[160:163], v[184:187], v[104:107]
	v_mfma_f32_16x16x32_bf16 v[104:107], v[164:167], v[188:191], v[104:107]
	v_mfma_f32_16x16x32_bf16 v[100:103], v[168:171], v[184:187], v[100:103]
	v_mfma_f32_16x16x32_bf16 v[100:103], v[172:175], v[188:191], v[100:103]
	v_mfma_f32_16x16x32_bf16 v[88:91], v[160:163], v[192:195], v[88:91]
	v_mfma_f32_16x16x32_bf16 v[88:91], v[164:167], v[196:199], v[88:91]
	v_mfma_f32_16x16x32_bf16 v[84:87], v[168:171], v[192:195], v[84:87]
	v_mfma_f32_16x16x32_bf16 v[84:87], v[172:175], v[196:199], v[84:87]
	v_mfma_f32_16x16x32_bf16 v[72:75], v[160:163], v[200:203], v[72:75]
	v_mfma_f32_16x16x32_bf16 v[72:75], v[164:167], v[204:207], v[72:75]
	v_mfma_f32_16x16x32_bf16 v[68:71], v[168:171], v[200:203], v[68:71]
	v_mfma_f32_16x16x32_bf16 v[68:71], v[172:175], v[204:207], v[68:71]
	s_setprio 0
	s_barrier
	s_mov_b32 m0, s23
	v_lshl_add_u64 v[208:209], s[12:13], 0, v[2:3]
	s_add_u32 s52, s12, 0x80000
	ds_read_b128 v[176:179], v127 offset:16384
	ds_read_b128 v[180:183], v127 offset:17408
	ds_read_b128 v[184:187], v127 offset:18432
	ds_read_b128 v[188:191], v127 offset:19456
	ds_read_b128 v[192:195], v127 offset:20480
	ds_read_b128 v[196:199], v127 offset:21504
	ds_read_b128 v[200:203], v127 offset:22528
	ds_read_b128 v[204:207], v127 offset:23552
	global_load_lds_dwordx4 v[208:209], off
	v_lshl_add_u64 v[210:211], s[12:13], 0, v[120:121]
	s_mov_b32 m0, s24
	s_addc_u32 s53, s13, 0
	global_load_lds_dwordx4 v[210:211], off
	v_lshl_add_u64 v[216:217], s[52:53], 0, v[2:3]
	s_mov_b32 m0, s25
	v_lshl_add_u64 v[218:219], s[14:15], 0, v[118:119]
	global_load_lds_dwordx4 v[216:217], off
	v_lshl_add_u64 v[216:217], s[52:53], 0, v[120:121]
	s_mov_b32 m0, s26
	s_nop 0
	global_load_lds_dwordx4 v[216:217], off
	v_lshl_add_u64 v[216:217], s[14:15], 0, v[116:117]
	s_mov_b32 m0, s27
	s_nop 0
	global_load_lds_dwordx4 v[216:217], off
	s_mov_b32 m0, s35
	s_nop 0
	global_load_lds_dwordx4 v[218:219], off
	s_waitcnt vmcnt(8)
	s_waitcnt lgkmcnt(0)
	s_barrier
	s_setprio 1
	s_waitcnt lgkmcnt(0)
	v_mfma_f32_16x16x32_bf16 v[64:67], v[128:131], v[176:179], v[64:67]
	v_mfma_f32_16x16x32_bf16 v[64:67], v[132:135], v[180:183], v[64:67]
	v_mfma_f32_16x16x32_bf16 v[60:63], v[140:143], v[176:179], v[60:63]
	v_mfma_f32_16x16x32_bf16 v[60:63], v[148:151], v[180:183], v[60:63]
	v_mfma_f32_16x16x32_bf16 v[48:51], v[128:131], v[184:187], v[48:51]
	v_mfma_f32_16x16x32_bf16 v[48:51], v[132:135], v[188:191], v[48:51]
	v_mfma_f32_16x16x32_bf16 v[44:47], v[140:143], v[184:187], v[44:47]
	v_mfma_f32_16x16x32_bf16 v[44:47], v[148:151], v[188:191], v[44:47]
	v_mfma_f32_16x16x32_bf16 v[32:35], v[128:131], v[192:195], v[32:35]
	v_mfma_f32_16x16x32_bf16 v[32:35], v[132:135], v[196:199], v[32:35]
	v_mfma_f32_16x16x32_bf16 v[28:31], v[140:143], v[192:195], v[28:31]
	v_mfma_f32_16x16x32_bf16 v[28:31], v[148:151], v[196:199], v[28:31]
	v_mfma_f32_16x16x32_bf16 v[16:19], v[128:131], v[200:203], v[16:19]
	v_mfma_f32_16x16x32_bf16 v[16:19], v[132:135], v[204:207], v[16:19]
	v_mfma_f32_16x16x32_bf16 v[12:15], v[140:143], v[200:203], v[12:15]
	v_mfma_f32_16x16x32_bf16 v[12:15], v[148:151], v[204:207], v[12:15]
	s_setprio 0
	s_setprio 1
	v_mfma_f32_16x16x32_bf16 v[56:59], v[160:163], v[176:179], v[56:59]
	v_mfma_f32_16x16x32_bf16 v[56:59], v[164:167], v[180:183], v[56:59]
	v_mfma_f32_16x16x32_bf16 v[52:55], v[168:171], v[176:179], v[52:55]
	v_mfma_f32_16x16x32_bf16 v[52:55], v[172:175], v[180:183], v[52:55]
	v_mfma_f32_16x16x32_bf16 v[40:43], v[160:163], v[184:187], v[40:43]
	v_mfma_f32_16x16x32_bf16 v[40:43], v[164:167], v[188:191], v[40:43]
	v_mfma_f32_16x16x32_bf16 v[36:39], v[168:171], v[184:187], v[36:39]
	v_mfma_f32_16x16x32_bf16 v[36:39], v[172:175], v[188:191], v[36:39]
	v_mfma_f32_16x16x32_bf16 v[24:27], v[160:163], v[192:195], v[24:27]
	v_mfma_f32_16x16x32_bf16 v[24:27], v[164:167], v[196:199], v[24:27]
	v_mfma_f32_16x16x32_bf16 v[20:23], v[168:171], v[192:195], v[20:23]
	v_mfma_f32_16x16x32_bf16 v[20:23], v[172:175], v[196:199], v[20:23]
	v_mfma_f32_16x16x32_bf16 v[8:11], v[160:163], v[200:203], v[8:11]
	v_mfma_f32_16x16x32_bf16 v[8:11], v[164:167], v[204:207], v[8:11]
	v_mfma_f32_16x16x32_bf16 v[4:7], v[168:171], v[200:203], v[4:7]
	v_mfma_f32_16x16x32_bf16 v[4:7], v[172:175], v[204:207], v[4:7]
	s_setprio 0
	s_barrier
	v_add_u32_e32 v148, s20, v126
	v_add_u32_e32 v172, s21, v126
	ds_read_b128 v[128:131], v148
	ds_read_b128 v[132:135], v148 offset:1024
	ds_read_b128 v[140:143], v148 offset:2048
	ds_read_b128 v[148:151], v148 offset:3072
	ds_read_b128 v[160:163], v172
	ds_read_b128 v[164:167], v172 offset:1024
	ds_read_b128 v[168:171], v172 offset:2048
	ds_read_b128 v[172:175], v172 offset:3072
	s_add_u32 s14, s14, 0x80000
	s_addc_u32 s15, s15, 0
	s_mov_b32 m0, s37
	v_lshl_add_u64 v[220:221], s[14:15], 0, v[116:117]
	ds_read_b128 v[176:179], v127 offset:32768
	ds_read_b128 v[180:183], v127 offset:33792
	ds_read_b128 v[184:187], v127 offset:34816
	ds_read_b128 v[188:191], v127 offset:35840
	ds_read_b128 v[192:195], v127 offset:36864
	ds_read_b128 v[196:199], v127 offset:37888
	ds_read_b128 v[200:203], v127 offset:38912
	ds_read_b128 v[204:207], v127 offset:39936
	global_load_lds_dwordx4 v[220:221], off
	v_lshl_add_u64 v[220:221], s[14:15], 0, v[118:119]
	s_mov_b32 m0, s38
	s_nop 0
	global_load_lds_dwordx4 v[220:221], off
	s_waitcnt vmcnt(8)
	s_waitcnt lgkmcnt(0)
	s_barrier
	s_setprio 1
	s_waitcnt lgkmcnt(0)
	v_mfma_f32_16x16x32_bf16 v[156:159], v[128:131], v[176:179], v[156:159]
	v_mfma_f32_16x16x32_bf16 v[156:159], v[132:135], v[180:183], v[156:159]
	v_mfma_f32_16x16x32_bf16 v[152:155], v[140:143], v[176:179], v[152:155]
	v_mfma_f32_16x16x32_bf16 v[152:155], v[148:151], v[180:183], v[152:155]
	v_mfma_f32_16x16x32_bf16 v[112:115], v[128:131], v[184:187], v[112:115]
	v_mfma_f32_16x16x32_bf16 v[112:115], v[132:135], v[188:191], v[112:115]
	v_mfma_f32_16x16x32_bf16 v[108:111], v[140:143], v[184:187], v[108:111]
	v_mfma_f32_16x16x32_bf16 v[108:111], v[148:151], v[188:191], v[108:111]
	v_mfma_f32_16x16x32_bf16 v[96:99], v[128:131], v[192:195], v[96:99]
	v_mfma_f32_16x16x32_bf16 v[96:99], v[132:135], v[196:199], v[96:99]
	v_mfma_f32_16x16x32_bf16 v[92:95], v[140:143], v[192:195], v[92:95]
	v_mfma_f32_16x16x32_bf16 v[92:95], v[148:151], v[196:199], v[92:95]
	v_mfma_f32_16x16x32_bf16 v[80:83], v[128:131], v[200:203], v[80:83]
	v_mfma_f32_16x16x32_bf16 v[80:83], v[132:135], v[204:207], v[80:83]
	v_mfma_f32_16x16x32_bf16 v[76:79], v[140:143], v[200:203], v[76:79]
	v_mfma_f32_16x16x32_bf16 v[76:79], v[148:151], v[204:207], v[76:79]
	s_setprio 0
	s_setprio 1
	v_mfma_f32_16x16x32_bf16 v[144:147], v[160:163], v[176:179], v[144:147]
	v_mfma_f32_16x16x32_bf16 v[144:147], v[164:167], v[180:183], v[144:147]
	v_mfma_f32_16x16x32_bf16 v[136:139], v[168:171], v[176:179], v[136:139]
	v_mfma_f32_16x16x32_bf16 v[136:139], v[172:175], v[180:183], v[136:139]
	v_mfma_f32_16x16x32_bf16 v[104:107], v[160:163], v[184:187], v[104:107]
	v_mfma_f32_16x16x32_bf16 v[104:107], v[164:167], v[188:191], v[104:107]
	v_mfma_f32_16x16x32_bf16 v[100:103], v[168:171], v[184:187], v[100:103]
	v_mfma_f32_16x16x32_bf16 v[100:103], v[172:175], v[188:191], v[100:103]
	v_mfma_f32_16x16x32_bf16 v[88:91], v[160:163], v[192:195], v[88:91]
	v_mfma_f32_16x16x32_bf16 v[88:91], v[164:167], v[196:199], v[88:91]
	v_mfma_f32_16x16x32_bf16 v[84:87], v[168:171], v[192:195], v[84:87]
	v_mfma_f32_16x16x32_bf16 v[84:87], v[172:175], v[196:199], v[84:87]
	v_mfma_f32_16x16x32_bf16 v[72:75], v[160:163], v[200:203], v[72:75]
	v_mfma_f32_16x16x32_bf16 v[72:75], v[164:167], v[204:207], v[72:75]
	v_mfma_f32_16x16x32_bf16 v[68:71], v[168:171], v[200:203], v[68:71]
	v_mfma_f32_16x16x32_bf16 v[68:71], v[172:175], v[204:207], v[68:71]
	s_setprio 0
	s_barrier
	s_mov_b32 m0, s40
	v_lshl_add_u64 v[208:209], v[208:209], 0, s[64:65]
	s_add_u32 s12, s12, 0x80080
	ds_read_b128 v[176:179], v127 offset:49152
	ds_read_b128 v[180:183], v127 offset:50176
	ds_read_b128 v[184:187], v127 offset:51200
	ds_read_b128 v[188:191], v127 offset:52224
	ds_read_b128 v[192:195], v127 offset:53248
	ds_read_b128 v[196:199], v127 offset:54272
	ds_read_b128 v[200:203], v127 offset:55296
	ds_read_b128 v[204:207], v127 offset:56320
	global_load_lds_dwordx4 v[208:209], off
	v_lshl_add_u64 v[208:209], v[210:211], 0, s[64:65]
	s_mov_b32 m0, s41
	s_addc_u32 s13, s13, 0
	global_load_lds_dwordx4 v[208:209], off
	v_lshl_add_u64 v[208:209], s[12:13], 0, v[2:3]
	s_mov_b32 m0, s44
	s_nop 0
	global_load_lds_dwordx4 v[208:209], off
	v_lshl_add_u64 v[208:209], s[12:13], 0, v[120:121]
	s_mov_b32 m0, s45
	s_nop 0
	global_load_lds_dwordx4 v[208:209], off
	v_lshl_add_u64 v[208:209], v[216:217], 0, s[64:65]
	s_mov_b32 m0, s42
	s_nop 0
	global_load_lds_dwordx4 v[208:209], off
	v_lshl_add_u64 v[208:209], v[218:219], 0, s[64:65]
	s_mov_b32 m0, s43
	s_nop 0
	global_load_lds_dwordx4 v[208:209], off
	s_waitcnt vmcnt(8)
	s_waitcnt lgkmcnt(0)
	s_barrier
	s_setprio 1
	s_waitcnt lgkmcnt(0)
	v_mfma_f32_16x16x32_bf16 v[64:67], v[128:131], v[176:179], v[64:67]
	v_mfma_f32_16x16x32_bf16 v[64:67], v[132:135], v[180:183], v[64:67]
	v_mfma_f32_16x16x32_bf16 v[60:63], v[140:143], v[176:179], v[60:63]
	v_mfma_f32_16x16x32_bf16 v[60:63], v[148:151], v[180:183], v[60:63]
	v_mfma_f32_16x16x32_bf16 v[48:51], v[128:131], v[184:187], v[48:51]
	v_mfma_f32_16x16x32_bf16 v[48:51], v[132:135], v[188:191], v[48:51]
	v_mfma_f32_16x16x32_bf16 v[44:47], v[140:143], v[184:187], v[44:47]
	v_mfma_f32_16x16x32_bf16 v[44:47], v[148:151], v[188:191], v[44:47]
	v_mfma_f32_16x16x32_bf16 v[32:35], v[128:131], v[192:195], v[32:35]
	v_mfma_f32_16x16x32_bf16 v[32:35], v[132:135], v[196:199], v[32:35]
	v_mfma_f32_16x16x32_bf16 v[28:31], v[140:143], v[192:195], v[28:31]
	v_mfma_f32_16x16x32_bf16 v[28:31], v[148:151], v[196:199], v[28:31]
	v_mfma_f32_16x16x32_bf16 v[16:19], v[128:131], v[200:203], v[16:19]
	v_mfma_f32_16x16x32_bf16 v[16:19], v[132:135], v[204:207], v[16:19]
	v_mfma_f32_16x16x32_bf16 v[12:15], v[140:143], v[200:203], v[12:15]
	v_mfma_f32_16x16x32_bf16 v[12:15], v[148:151], v[204:207], v[12:15]
	s_setprio 0
	s_setprio 1
	v_mfma_f32_16x16x32_bf16 v[56:59], v[160:163], v[176:179], v[56:59]
	v_mfma_f32_16x16x32_bf16 v[56:59], v[164:167], v[180:183], v[56:59]
	v_mfma_f32_16x16x32_bf16 v[52:55], v[168:171], v[176:179], v[52:55]
	v_mfma_f32_16x16x32_bf16 v[52:55], v[172:175], v[180:183], v[52:55]
	v_mfma_f32_16x16x32_bf16 v[40:43], v[160:163], v[184:187], v[40:43]
	v_mfma_f32_16x16x32_bf16 v[40:43], v[164:167], v[188:191], v[40:43]
	v_mfma_f32_16x16x32_bf16 v[36:39], v[168:171], v[184:187], v[36:39]
	v_mfma_f32_16x16x32_bf16 v[36:39], v[172:175], v[188:191], v[36:39]
	v_mfma_f32_16x16x32_bf16 v[24:27], v[160:163], v[192:195], v[24:27]
	v_mfma_f32_16x16x32_bf16 v[24:27], v[164:167], v[196:199], v[24:27]
	v_mfma_f32_16x16x32_bf16 v[20:23], v[168:171], v[192:195], v[20:23]
	v_mfma_f32_16x16x32_bf16 v[20:23], v[172:175], v[196:199], v[20:23]
	v_mfma_f32_16x16x32_bf16 v[8:11], v[160:163], v[200:203], v[8:11]
	v_mfma_f32_16x16x32_bf16 v[8:11], v[164:167], v[204:207], v[8:11]
	v_mfma_f32_16x16x32_bf16 v[4:7], v[168:171], v[200:203], v[4:7]
	v_mfma_f32_16x16x32_bf16 v[4:7], v[172:175], v[204:207], v[4:7]
	s_setprio 0
	s_barrier
	s_add_i32 s50, s50, 2
	s_add_u32 s8, s8, 0x100
	s_addc_u32 s9, s9, 0
	s_cmp_gt_u32 s50, 29
	s_cbranch_scc0 .LBB0_2896
	s_cmpk_lt_u32 s22, 0x100
	s_cbranch_scc0 .LBB0_2899
	s_barrier

.LBB0_3116:
	v_add_u32_e32 v142, s26, v144
	ds_read_b128 v[146:149], v142
	ds_read_b128 v[150:153], v142 offset:1024
	ds_read_b128 v[154:157], v142 offset:2048
	ds_read_b128 v[158:161], v142 offset:3072
	v_add_u32_e32 v142, s40, v144
	ds_read_b128 v[162:165], v142
	ds_read_b128 v[166:169], v142 offset:1024
	ds_read_b128 v[170:173], v142 offset:2048
	ds_read_b128 v[174:177], v142 offset:3072
	s_add_u32 s18, s34, 0xfff80080
	s_addc_u32 s19, s35, -1
	s_cmp_eq_u32 s74, 28
	s_cselect_b32 s39, s13, s19
	s_cselect_b32 s38, s69, s18
	s_cselect_b32 s19, s11, s73
	s_cselect_b32 s18, s70, s71
	v_lshl_add_u64 v[142:143], s[34:35], 0, v[138:139]
	s_add_i32 m0, s43, 0xc000
	ds_read_b128 v[178:181], v145
	ds_read_b128 v[182:185], v145 offset:1024
	ds_read_b128 v[186:189], v145 offset:2048
	ds_read_b128 v[190:193], v145 offset:3072
	ds_read_b128 v[194:197], v145 offset:4096
	ds_read_b128 v[198:201], v145 offset:5120
	ds_read_b128 v[202:205], v145 offset:6144
	ds_read_b128 v[206:209], v145 offset:7168
	global_load_lds_dwordx4 v[142:143], off
	v_lshl_add_u64 v[142:143], s[34:35], 0, v[140:141]
	s_add_i32 m0, s43, 0xe000
	s_nop 0
	global_load_lds_dwordx4 v[142:143], off
	s_waitcnt vmcnt(8)
	s_waitcnt lgkmcnt(0)
	s_barrier
	s_setprio 1
	s_waitcnt lgkmcnt(0)
	v_mfma_f32_16x16x32_bf16 v[128:131], v[146:149], v[178:181], v[128:131]
	v_mfma_f32_16x16x32_bf16 v[128:131], v[150:153], v[182:185], v[128:131]
	v_mfma_f32_16x16x32_bf16 v[120:123], v[154:157], v[178:181], v[120:123]
	v_mfma_f32_16x16x32_bf16 v[120:123], v[158:161], v[182:185], v[120:123]
	v_mfma_f32_16x16x32_bf16 v[112:115], v[146:149], v[186:189], v[112:115]
	v_mfma_f32_16x16x32_bf16 v[112:115], v[150:153], v[190:193], v[112:115]
	v_mfma_f32_16x16x32_bf16 v[104:107], v[154:157], v[186:189], v[104:107]
	v_mfma_f32_16x16x32_bf16 v[104:107], v[158:161], v[190:193], v[104:107]
	v_mfma_f32_16x16x32_bf16 v[96:99], v[146:149], v[194:197], v[96:99]
	v_mfma_f32_16x16x32_bf16 v[96:99], v[150:153], v[198:201], v[96:99]
	v_mfma_f32_16x16x32_bf16 v[88:91], v[154:157], v[194:197], v[88:91]
	v_mfma_f32_16x16x32_bf16 v[88:91], v[158:161], v[198:201], v[88:91]
	v_mfma_f32_16x16x32_bf16 v[80:83], v[146:149], v[202:205], v[80:83]
	v_mfma_f32_16x16x32_bf16 v[80:83], v[150:153], v[206:209], v[80:83]
	v_mfma_f32_16x16x32_bf16 v[72:75], v[154:157], v[202:205], v[72:75]
	v_mfma_f32_16x16x32_bf16 v[72:75], v[158:161], v[206:209], v[72:75]
	s_setprio 0
	s_setprio 1
	v_mfma_f32_16x16x32_bf16 v[124:127], v[162:165], v[178:181], v[124:127]
	v_mfma_f32_16x16x32_bf16 v[124:127], v[166:169], v[182:185], v[124:127]
	v_mfma_f32_16x16x32_bf16 v[116:119], v[170:173], v[178:181], v[116:119]
	v_mfma_f32_16x16x32_bf16 v[116:119], v[174:177], v[182:185], v[116:119]
	v_mfma_f32_16x16x32_bf16 v[108:111], v[162:165], v[186:189], v[108:111]
	v_mfma_f32_16x16x32_bf16 v[108:111], v[166:169], v[190:193], v[108:111]
	v_mfma_f32_16x16x32_bf16 v[100:103], v[170:173], v[186:189], v[100:103]
	v_mfma_f32_16x16x32_bf16 v[100:103], v[174:177], v[190:193], v[100:103]
	v_mfma_f32_16x16x32_bf16 v[92:95], v[162:165], v[194:197], v[92:95]
	v_mfma_f32_16x16x32_bf16 v[92:95], v[166:169], v[198:201], v[92:95]
	v_mfma_f32_16x16x32_bf16 v[84:87], v[170:173], v[194:197], v[84:87]
	v_mfma_f32_16x16x32_bf16 v[84:87], v[174:177], v[198:201], v[84:87]
	v_mfma_f32_16x16x32_bf16 v[76:79], v[162:165], v[202:205], v[76:79]
	v_mfma_f32_16x16x32_bf16 v[76:79], v[166:169], v[206:209], v[76:79]
	v_mfma_f32_16x16x32_bf16 v[68:71], v[170:173], v[202:205], v[68:71]
	v_mfma_f32_16x16x32_bf16 v[68:71], v[174:177], v[206:209], v[68:71]
	s_setprio 0
	s_barrier
	s_mov_b32 m0, s27
	v_lshl_add_u64 v[142:143], s[18:19], 0, v[2:3]
	s_add_u32 s76, s18, 0x80000
	ds_read_b128 v[178:181], v145 offset:16384
	ds_read_b128 v[182:185], v145 offset:17408
	ds_read_b128 v[186:189], v145 offset:18432
	ds_read_b128 v[190:193], v145 offset:19456
	ds_read_b128 v[194:197], v145 offset:20480
	ds_read_b128 v[198:201], v145 offset:21504
	ds_read_b128 v[202:205], v145 offset:22528
	ds_read_b128 v[206:209], v145 offset:23552
	global_load_lds_dwordx4 v[142:143], off
	v_lshl_add_u64 v[210:211], s[18:19], 0, v[132:133]
	s_mov_b32 m0, s37
	s_addc_u32 s77, s19, 0
	global_load_lds_dwordx4 v[210:211], off
	v_lshl_add_u64 v[212:213], s[76:77], 0, v[2:3]
	s_mov_b32 m0, s41
	v_lshl_add_u64 v[214:215], s[38:39], 0, v[134:135]
	global_load_lds_dwordx4 v[212:213], off
	v_lshl_add_u64 v[212:213], s[76:77], 0, v[132:133]
	s_mov_b32 m0, s42
	s_nop 0
	global_load_lds_dwordx4 v[212:213], off
	v_lshl_add_u64 v[212:213], s[38:39], 0, v[136:137]
	s_mov_b32 m0, s43
	s_nop 0
	global_load_lds_dwordx4 v[212:213], off
	s_mov_b32 m0, s44
	s_nop 0
	global_load_lds_dwordx4 v[214:215], off
	s_waitcnt vmcnt(8)
	s_waitcnt lgkmcnt(0)
	s_barrier
	s_setprio 1
	s_waitcnt lgkmcnt(0)
	v_mfma_f32_16x16x32_bf16 v[64:67], v[146:149], v[178:181], v[64:67]
	v_mfma_f32_16x16x32_bf16 v[64:67], v[150:153], v[182:185], v[64:67]
	v_mfma_f32_16x16x32_bf16 v[56:59], v[154:157], v[178:181], v[56:59]
	v_mfma_f32_16x16x32_bf16 v[56:59], v[158:161], v[182:185], v[56:59]
	v_mfma_f32_16x16x32_bf16 v[48:51], v[146:149], v[186:189], v[48:51]
	v_mfma_f32_16x16x32_bf16 v[48:51], v[150:153], v[190:193], v[48:51]
	v_mfma_f32_16x16x32_bf16 v[40:43], v[154:157], v[186:189], v[40:43]
	v_mfma_f32_16x16x32_bf16 v[40:43], v[158:161], v[190:193], v[40:43]
	v_mfma_f32_16x16x32_bf16 v[32:35], v[146:149], v[194:197], v[32:35]
	v_mfma_f32_16x16x32_bf16 v[32:35], v[150:153], v[198:201], v[32:35]
	v_mfma_f32_16x16x32_bf16 v[24:27], v[154:157], v[194:197], v[24:27]
	v_mfma_f32_16x16x32_bf16 v[24:27], v[158:161], v[198:201], v[24:27]
	v_mfma_f32_16x16x32_bf16 v[16:19], v[146:149], v[202:205], v[16:19]
	v_mfma_f32_16x16x32_bf16 v[16:19], v[150:153], v[206:209], v[16:19]
	v_mfma_f32_16x16x32_bf16 v[8:11], v[154:157], v[202:205], v[8:11]
	v_mfma_f32_16x16x32_bf16 v[8:11], v[158:161], v[206:209], v[8:11]
	s_setprio 0
	s_setprio 1
	v_mfma_f32_16x16x32_bf16 v[60:63], v[162:165], v[178:181], v[60:63]
	v_mfma_f32_16x16x32_bf16 v[60:63], v[166:169], v[182:185], v[60:63]
	v_mfma_f32_16x16x32_bf16 v[52:55], v[170:173], v[178:181], v[52:55]
	v_mfma_f32_16x16x32_bf16 v[52:55], v[174:177], v[182:185], v[52:55]
	v_mfma_f32_16x16x32_bf16 v[44:47], v[162:165], v[186:189], v[44:47]
	v_mfma_f32_16x16x32_bf16 v[44:47], v[166:169], v[190:193], v[44:47]
	v_mfma_f32_16x16x32_bf16 v[36:39], v[170:173], v[186:189], v[36:39]
	v_mfma_f32_16x16x32_bf16 v[36:39], v[174:177], v[190:193], v[36:39]
	v_mfma_f32_16x16x32_bf16 v[28:31], v[162:165], v[194:197], v[28:31]
	v_mfma_f32_16x16x32_bf16 v[28:31], v[166:169], v[198:201], v[28:31]
	v_mfma_f32_16x16x32_bf16 v[20:23], v[170:173], v[194:197], v[20:23]
	v_mfma_f32_16x16x32_bf16 v[20:23], v[174:177], v[198:201], v[20:23]
	v_mfma_f32_16x16x32_bf16 v[12:15], v[162:165], v[202:205], v[12:15]
	v_mfma_f32_16x16x32_bf16 v[12:15], v[166:169], v[206:209], v[12:15]
	v_mfma_f32_16x16x32_bf16 v[4:7], v[170:173], v[202:205], v[4:7]
	v_mfma_f32_16x16x32_bf16 v[4:7], v[174:177], v[206:209], v[4:7]
	s_setprio 0
	s_barrier
	v_add_u32_e32 v158, s49, v144
	v_add_u32_e32 v174, s56, v144
	ds_read_b128 v[146:149], v158
	ds_read_b128 v[150:153], v158 offset:1024
	ds_read_b128 v[154:157], v158 offset:2048
	ds_read_b128 v[158:161], v158 offset:3072
	ds_read_b128 v[162:165], v174
	ds_read_b128 v[166:169], v174 offset:1024
	ds_read_b128 v[170:173], v174 offset:2048
	ds_read_b128 v[174:177], v174 offset:3072
	s_add_u32 s38, s38, 0x80000
	s_addc_u32 s39, s39, 0
	s_mov_b32 m0, s45
	v_lshl_add_u64 v[216:217], s[38:39], 0, v[136:137]
	ds_read_b128 v[178:181], v145 offset:32768
	ds_read_b128 v[182:185], v145 offset:33792
	ds_read_b128 v[186:189], v145 offset:34816
	ds_read_b128 v[190:193], v145 offset:35840
	ds_read_b128 v[194:197], v145 offset:36864
	ds_read_b128 v[198:201], v145 offset:37888
	ds_read_b128 v[202:205], v145 offset:38912
	ds_read_b128 v[206:209], v145 offset:39936
	global_load_lds_dwordx4 v[216:217], off
	v_lshl_add_u64 v[216:217], s[38:39], 0, v[134:135]
	s_mov_b32 m0, s46
	s_nop 0
	global_load_lds_dwordx4 v[216:217], off
	s_waitcnt vmcnt(8)
	s_waitcnt lgkmcnt(0)
	s_barrier
	s_setprio 1
	s_waitcnt lgkmcnt(0)
	v_mfma_f32_16x16x32_bf16 v[128:131], v[146:149], v[178:181], v[128:131]
	v_mfma_f32_16x16x32_bf16 v[128:131], v[150:153], v[182:185], v[128:131]
	v_mfma_f32_16x16x32_bf16 v[120:123], v[154:157], v[178:181], v[120:123]
	v_mfma_f32_16x16x32_bf16 v[120:123], v[158:161], v[182:185], v[120:123]
	v_mfma_f32_16x16x32_bf16 v[112:115], v[146:149], v[186:189], v[112:115]
	v_mfma_f32_16x16x32_bf16 v[112:115], v[150:153], v[190:193], v[112:115]
	v_mfma_f32_16x16x32_bf16 v[104:107], v[154:157], v[186:189], v[104:107]
	v_mfma_f32_16x16x32_bf16 v[104:107], v[158:161], v[190:193], v[104:107]
	v_mfma_f32_16x16x32_bf16 v[96:99], v[146:149], v[194:197], v[96:99]
	v_mfma_f32_16x16x32_bf16 v[96:99], v[150:153], v[198:201], v[96:99]
	v_mfma_f32_16x16x32_bf16 v[88:91], v[154:157], v[194:197], v[88:91]
	v_mfma_f32_16x16x32_bf16 v[88:91], v[158:161], v[198:201], v[88:91]
	v_mfma_f32_16x16x32_bf16 v[80:83], v[146:149], v[202:205], v[80:83]
	v_mfma_f32_16x16x32_bf16 v[80:83], v[150:153], v[206:209], v[80:83]
	v_mfma_f32_16x16x32_bf16 v[72:75], v[154:157], v[202:205], v[72:75]
	v_mfma_f32_16x16x32_bf16 v[72:75], v[158:161], v[206:209], v[72:75]
	s_setprio 0
	s_setprio 1
	v_mfma_f32_16x16x32_bf16 v[124:127], v[162:165], v[178:181], v[124:127]
	v_mfma_f32_16x16x32_bf16 v[124:127], v[166:169], v[182:185], v[124:127]
	v_mfma_f32_16x16x32_bf16 v[116:119], v[170:173], v[178:181], v[116:119]
	v_mfma_f32_16x16x32_bf16 v[116:119], v[174:177], v[182:185], v[116:119]
	v_mfma_f32_16x16x32_bf16 v[108:111], v[162:165], v[186:189], v[108:111]
	v_mfma_f32_16x16x32_bf16 v[108:111], v[166:169], v[190:193], v[108:111]
	v_mfma_f32_16x16x32_bf16 v[100:103], v[170:173], v[186:189], v[100:103]
	v_mfma_f32_16x16x32_bf16 v[100:103], v[174:177], v[190:193], v[100:103]
	v_mfma_f32_16x16x32_bf16 v[92:95], v[162:165], v[194:197], v[92:95]
	v_mfma_f32_16x16x32_bf16 v[92:95], v[166:169], v[198:201], v[92:95]
	v_mfma_f32_16x16x32_bf16 v[84:87], v[170:173], v[194:197], v[84:87]
	v_mfma_f32_16x16x32_bf16 v[84:87], v[174:177], v[198:201], v[84:87]
	v_mfma_f32_16x16x32_bf16 v[76:79], v[162:165], v[202:205], v[76:79]
	v_mfma_f32_16x16x32_bf16 v[76:79], v[166:169], v[206:209], v[76:79]
	v_mfma_f32_16x16x32_bf16 v[68:71], v[170:173], v[202:205], v[68:71]
	v_mfma_f32_16x16x32_bf16 v[68:71], v[174:177], v[206:209], v[68:71]
	s_setprio 0
	s_barrier
	s_mov_b32 m0, s50
	v_lshl_add_u64 v[142:143], v[142:143], 0, s[64:65]
	s_add_u32 s18, s18, 0x80080
	ds_read_b128 v[178:181], v145 offset:49152
	ds_read_b128 v[182:185], v145 offset:50176
	ds_read_b128 v[186:189], v145 offset:51200
	ds_read_b128 v[190:193], v145 offset:52224
	ds_read_b128 v[194:197], v145 offset:53248
	ds_read_b128 v[198:201], v145 offset:54272
	ds_read_b128 v[202:205], v145 offset:55296
	ds_read_b128 v[206:209], v145 offset:56320
	global_load_lds_dwordx4 v[142:143], off
	v_lshl_add_u64 v[142:143], v[210:211], 0, s[64:65]
	s_mov_b32 m0, s51
	s_addc_u32 s19, s19, 0
	global_load_lds_dwordx4 v[142:143], off
	v_lshl_add_u64 v[142:143], s[18:19], 0, v[2:3]
	s_mov_b32 m0, s57
	s_nop 0
	global_load_lds_dwordx4 v[142:143], off
	v_lshl_add_u64 v[142:143], s[18:19], 0, v[132:133]
	s_mov_b32 m0, s58
	s_nop 0
	global_load_lds_dwordx4 v[142:143], off
	v_lshl_add_u64 v[142:143], v[212:213], 0, s[64:65]
	s_mov_b32 m0, s52
	s_nop 0
	global_load_lds_dwordx4 v[142:143], off
	v_lshl_add_u64 v[142:143], v[214:215], 0, s[64:65]
	s_mov_b32 m0, s53
	s_nop 0
	global_load_lds_dwordx4 v[142:143], off
	s_waitcnt vmcnt(8)
	s_waitcnt lgkmcnt(0)
	s_barrier
	s_setprio 1
	s_waitcnt lgkmcnt(0)
	v_mfma_f32_16x16x32_bf16 v[64:67], v[146:149], v[178:181], v[64:67]
	v_mfma_f32_16x16x32_bf16 v[64:67], v[150:153], v[182:185], v[64:67]
	v_mfma_f32_16x16x32_bf16 v[56:59], v[154:157], v[178:181], v[56:59]
	v_mfma_f32_16x16x32_bf16 v[56:59], v[158:161], v[182:185], v[56:59]
	v_mfma_f32_16x16x32_bf16 v[48:51], v[146:149], v[186:189], v[48:51]
	v_mfma_f32_16x16x32_bf16 v[48:51], v[150:153], v[190:193], v[48:51]
	v_mfma_f32_16x16x32_bf16 v[40:43], v[154:157], v[186:189], v[40:43]
	v_mfma_f32_16x16x32_bf16 v[40:43], v[158:161], v[190:193], v[40:43]
	v_mfma_f32_16x16x32_bf16 v[32:35], v[146:149], v[194:197], v[32:35]
	v_mfma_f32_16x16x32_bf16 v[32:35], v[150:153], v[198:201], v[32:35]
	v_mfma_f32_16x16x32_bf16 v[24:27], v[154:157], v[194:197], v[24:27]
	v_mfma_f32_16x16x32_bf16 v[24:27], v[158:161], v[198:201], v[24:27]
	v_mfma_f32_16x16x32_bf16 v[16:19], v[146:149], v[202:205], v[16:19]
	v_mfma_f32_16x16x32_bf16 v[16:19], v[150:153], v[206:209], v[16:19]
	v_mfma_f32_16x16x32_bf16 v[8:11], v[154:157], v[202:205], v[8:11]
	v_mfma_f32_16x16x32_bf16 v[8:11], v[158:161], v[206:209], v[8:11]
	s_setprio 0
	s_setprio 1
	v_mfma_f32_16x16x32_bf16 v[60:63], v[162:165], v[178:181], v[60:63]
	v_mfma_f32_16x16x32_bf16 v[60:63], v[166:169], v[182:185], v[60:63]
	v_mfma_f32_16x16x32_bf16 v[52:55], v[170:173], v[178:181], v[52:55]
	v_mfma_f32_16x16x32_bf16 v[52:55], v[174:177], v[182:185], v[52:55]
	v_mfma_f32_16x16x32_bf16 v[44:47], v[162:165], v[186:189], v[44:47]
	v_mfma_f32_16x16x32_bf16 v[44:47], v[166:169], v[190:193], v[44:47]
	v_mfma_f32_16x16x32_bf16 v[36:39], v[170:173], v[186:189], v[36:39]
	v_mfma_f32_16x16x32_bf16 v[36:39], v[174:177], v[190:193], v[36:39]
	v_mfma_f32_16x16x32_bf16 v[28:31], v[162:165], v[194:197], v[28:31]
	v_mfma_f32_16x16x32_bf16 v[28:31], v[166:169], v[198:201], v[28:31]
	v_mfma_f32_16x16x32_bf16 v[20:23], v[170:173], v[194:197], v[20:23]
	v_mfma_f32_16x16x32_bf16 v[20:23], v[174:177], v[198:201], v[20:23]
	v_mfma_f32_16x16x32_bf16 v[12:15], v[162:165], v[202:205], v[12:15]
	v_mfma_f32_16x16x32_bf16 v[12:15], v[166:169], v[206:209], v[12:15]
	v_mfma_f32_16x16x32_bf16 v[4:7], v[170:173], v[202:205], v[4:7]
	v_mfma_f32_16x16x32_bf16 v[4:7], v[174:177], v[206:209], v[4:7]
	s_setprio 0
	s_barrier
	s_add_i32 s74, s74, 2
	s_add_u32 s34, s34, 0x100
	s_addc_u32 s35, s35, 0
	s_add_u32 s71, s71, 0x100
	s_addc_u32 s73, s73, 0
	s_cmp_gt_u32 s74, 29
	s_cbranch_scc0 .LBB0_3116
	s_and_b64 vcc, exec, s[8:9]
	s_cbranch_vccz .LBB0_3119
	s_barrier

.LBB0_3195:
	v_add_u32_e32 v144, s26, v249
	v_add_u32_e32 v160, s38, v249
	ds_read_b128 v[132:135], v144
	ds_read_b128 v[136:139], v144 offset:1024
	ds_read_b128 v[140:143], v144 offset:2048
	ds_read_b128 v[144:147], v144 offset:3072
	ds_read_b128 v[148:151], v160
	ds_read_b128 v[152:155], v160 offset:1024
	ds_read_b128 v[156:159], v160 offset:2048
	ds_read_b128 v[160:163], v160 offset:3072
	s_add_u32 s24, s14, 0x100
	s_addc_u32 s25, s15, 0
	s_cmpk_eq_i32 s74, 0x54
	s_cselect_b32 s35, s5, s25
	s_cselect_b32 s34, s4, s24
	s_cselect_b32 s19, s13, s73
	s_cselect_b32 s18, s12, s71
	v_lshl_add_u64 v[196:197], s[14:15], 0, v[222:223]
	s_add_i32 m0, s41, 0xc000
	ds_read_b128 v[164:167], v250
	ds_read_b128 v[168:171], v250 offset:1024
	ds_read_b128 v[172:175], v250 offset:2048
	ds_read_b128 v[176:179], v250 offset:3072
	ds_read_b128 v[180:183], v250 offset:4096
	ds_read_b128 v[184:187], v250 offset:5120
	ds_read_b128 v[188:191], v250 offset:6144
	ds_read_b128 v[192:195], v250 offset:7168
	global_load_lds_dwordx4 v[196:197], off
	v_lshl_add_u64 v[196:197], s[14:15], 0, v[224:225]
	s_add_i32 m0, s41, 0xe000
	s_nop 0
	global_load_lds_dwordx4 v[196:197], off
	s_waitcnt vmcnt(8)
	s_waitcnt lgkmcnt(0)
	s_barrier
	s_setprio 1
	s_waitcnt lgkmcnt(0)
	v_mfma_f32_16x16x32_bf16 v[128:131], v[132:135], v[164:167], v[128:131]
	v_mfma_f32_16x16x32_bf16 v[128:131], v[136:139], v[168:171], v[128:131]
	v_mfma_f32_16x16x32_bf16 v[124:127], v[140:143], v[164:167], v[124:127]
	v_mfma_f32_16x16x32_bf16 v[124:127], v[144:147], v[168:171], v[124:127]
	v_mfma_f32_16x16x32_bf16 v[112:115], v[132:135], v[172:175], v[112:115]
	v_mfma_f32_16x16x32_bf16 v[112:115], v[136:139], v[176:179], v[112:115]
	v_mfma_f32_16x16x32_bf16 v[108:111], v[140:143], v[172:175], v[108:111]
	v_mfma_f32_16x16x32_bf16 v[108:111], v[144:147], v[176:179], v[108:111]
	v_mfma_f32_16x16x32_bf16 v[96:99], v[132:135], v[180:183], v[96:99]
	v_mfma_f32_16x16x32_bf16 v[96:99], v[136:139], v[184:187], v[96:99]
	v_mfma_f32_16x16x32_bf16 v[92:95], v[140:143], v[180:183], v[92:95]
	v_mfma_f32_16x16x32_bf16 v[92:95], v[144:147], v[184:187], v[92:95]
	v_mfma_f32_16x16x32_bf16 v[80:83], v[132:135], v[188:191], v[80:83]
	v_mfma_f32_16x16x32_bf16 v[80:83], v[136:139], v[192:195], v[80:83]
	v_mfma_f32_16x16x32_bf16 v[76:79], v[140:143], v[188:191], v[76:79]
	v_mfma_f32_16x16x32_bf16 v[76:79], v[144:147], v[192:195], v[76:79]
	s_setprio 0
	s_setprio 1
	v_mfma_f32_16x16x32_bf16 v[120:123], v[148:151], v[164:167], v[120:123]
	v_mfma_f32_16x16x32_bf16 v[120:123], v[152:155], v[168:171], v[120:123]
	v_mfma_f32_16x16x32_bf16 v[116:119], v[156:159], v[164:167], v[116:119]
	v_mfma_f32_16x16x32_bf16 v[116:119], v[160:163], v[168:171], v[116:119]
	v_mfma_f32_16x16x32_bf16 v[104:107], v[148:151], v[172:175], v[104:107]
	v_mfma_f32_16x16x32_bf16 v[104:107], v[152:155], v[176:179], v[104:107]
	v_mfma_f32_16x16x32_bf16 v[100:103], v[156:159], v[172:175], v[100:103]
	v_mfma_f32_16x16x32_bf16 v[100:103], v[160:163], v[176:179], v[100:103]
	v_mfma_f32_16x16x32_bf16 v[88:91], v[148:151], v[180:183], v[88:91]
	v_mfma_f32_16x16x32_bf16 v[88:91], v[152:155], v[184:187], v[88:91]
	v_mfma_f32_16x16x32_bf16 v[84:87], v[156:159], v[180:183], v[84:87]
	v_mfma_f32_16x16x32_bf16 v[84:87], v[160:163], v[184:187], v[84:87]
	v_mfma_f32_16x16x32_bf16 v[72:75], v[148:151], v[188:191], v[72:75]
	v_mfma_f32_16x16x32_bf16 v[72:75], v[152:155], v[192:195], v[72:75]
	v_mfma_f32_16x16x32_bf16 v[68:71], v[156:159], v[188:191], v[68:71]
	v_mfma_f32_16x16x32_bf16 v[68:71], v[160:163], v[192:195], v[68:71]
	s_setprio 0
	s_barrier
	s_mov_b32 m0, s27
	v_lshl_add_u64 v[196:197], s[18:19], 0, v[2:3]
	s_add_u32 s14, s18, 0x160000
	ds_read_b128 v[164:167], v250 offset:16384
	ds_read_b128 v[168:171], v250 offset:17408
	ds_read_b128 v[172:175], v250 offset:18432
	ds_read_b128 v[176:179], v250 offset:19456
	ds_read_b128 v[180:183], v250 offset:20480
	ds_read_b128 v[184:187], v250 offset:21504
	ds_read_b128 v[188:191], v250 offset:22528
	ds_read_b128 v[192:195], v250 offset:23552
	global_load_lds_dwordx4 v[196:197], off
	v_lshl_add_u64 v[198:199], s[18:19], 0, v[216:217]
	s_mov_b32 m0, s37
	s_addc_u32 s15, s19, 0
	global_load_lds_dwordx4 v[198:199], off
	v_lshl_add_u64 v[200:201], s[14:15], 0, v[2:3]
	s_mov_b32 m0, s39
	v_lshl_add_u64 v[202:203], s[34:35], 0, v[218:219]
	global_load_lds_dwordx4 v[200:201], off
	v_lshl_add_u64 v[200:201], s[14:15], 0, v[216:217]
	s_mov_b32 m0, s40
	s_nop 0
	global_load_lds_dwordx4 v[200:201], off
	v_lshl_add_u64 v[200:201], s[34:35], 0, v[220:221]
	s_mov_b32 m0, s41
	s_nop 0
	global_load_lds_dwordx4 v[200:201], off
	s_mov_b32 m0, s42
	s_nop 0
	global_load_lds_dwordx4 v[202:203], off
	s_waitcnt vmcnt(8)
	s_waitcnt lgkmcnt(0)
	s_barrier
	s_setprio 1
	s_waitcnt lgkmcnt(0)
	v_mfma_f32_16x16x32_bf16 v[64:67], v[132:135], v[164:167], v[64:67]
	v_mfma_f32_16x16x32_bf16 v[64:67], v[136:139], v[168:171], v[64:67]
	v_mfma_f32_16x16x32_bf16 v[60:63], v[140:143], v[164:167], v[60:63]
	v_mfma_f32_16x16x32_bf16 v[60:63], v[144:147], v[168:171], v[60:63]
	v_mfma_f32_16x16x32_bf16 v[48:51], v[132:135], v[172:175], v[48:51]
	v_mfma_f32_16x16x32_bf16 v[48:51], v[136:139], v[176:179], v[48:51]
	v_mfma_f32_16x16x32_bf16 v[44:47], v[140:143], v[172:175], v[44:47]
	v_mfma_f32_16x16x32_bf16 v[44:47], v[144:147], v[176:179], v[44:47]
	v_mfma_f32_16x16x32_bf16 v[32:35], v[132:135], v[180:183], v[32:35]
	v_mfma_f32_16x16x32_bf16 v[32:35], v[136:139], v[184:187], v[32:35]
	v_mfma_f32_16x16x32_bf16 v[28:31], v[140:143], v[180:183], v[28:31]
	v_mfma_f32_16x16x32_bf16 v[28:31], v[144:147], v[184:187], v[28:31]
	v_mfma_f32_16x16x32_bf16 v[16:19], v[132:135], v[188:191], v[16:19]
	v_mfma_f32_16x16x32_bf16 v[16:19], v[136:139], v[192:195], v[16:19]
	v_mfma_f32_16x16x32_bf16 v[12:15], v[140:143], v[188:191], v[12:15]
	v_mfma_f32_16x16x32_bf16 v[12:15], v[144:147], v[192:195], v[12:15]
	s_setprio 0
	s_setprio 1
	v_mfma_f32_16x16x32_bf16 v[56:59], v[148:151], v[164:167], v[56:59]
	v_mfma_f32_16x16x32_bf16 v[56:59], v[152:155], v[168:171], v[56:59]
	v_mfma_f32_16x16x32_bf16 v[52:55], v[156:159], v[164:167], v[52:55]
	v_mfma_f32_16x16x32_bf16 v[52:55], v[160:163], v[168:171], v[52:55]
	v_mfma_f32_16x16x32_bf16 v[40:43], v[148:151], v[172:175], v[40:43]
	v_mfma_f32_16x16x32_bf16 v[40:43], v[152:155], v[176:179], v[40:43]
	v_mfma_f32_16x16x32_bf16 v[36:39], v[156:159], v[172:175], v[36:39]
	v_mfma_f32_16x16x32_bf16 v[36:39], v[160:163], v[176:179], v[36:39]
	v_mfma_f32_16x16x32_bf16 v[24:27], v[148:151], v[180:183], v[24:27]
	v_mfma_f32_16x16x32_bf16 v[24:27], v[152:155], v[184:187], v[24:27]
	v_mfma_f32_16x16x32_bf16 v[20:23], v[156:159], v[180:183], v[20:23]
	v_mfma_f32_16x16x32_bf16 v[20:23], v[160:163], v[184:187], v[20:23]
	v_mfma_f32_16x16x32_bf16 v[8:11], v[148:151], v[188:191], v[8:11]
	v_mfma_f32_16x16x32_bf16 v[8:11], v[152:155], v[192:195], v[8:11]
	v_mfma_f32_16x16x32_bf16 v[4:7], v[156:159], v[188:191], v[4:7]
	v_mfma_f32_16x16x32_bf16 v[4:7], v[160:163], v[192:195], v[4:7]
	s_setprio 0
	s_barrier
	v_add_u32_e32 v144, s49, v249
	v_add_u32_e32 v160, s56, v249
	ds_read_b128 v[132:135], v144
	ds_read_b128 v[136:139], v144 offset:1024
	ds_read_b128 v[140:143], v144 offset:2048
	ds_read_b128 v[144:147], v144 offset:3072
	ds_read_b128 v[148:151], v160
	ds_read_b128 v[152:155], v160 offset:1024
	ds_read_b128 v[156:159], v160 offset:2048
	ds_read_b128 v[160:163], v160 offset:3072
	s_add_u32 s14, s34, 0x160000
	s_addc_u32 s15, s35, 0
	s_mov_b32 m0, s43
	v_lshl_add_u64 v[204:205], s[14:15], 0, v[220:221]
	ds_read_b128 v[164:167], v250 offset:32768
	ds_read_b128 v[168:171], v250 offset:33792
	ds_read_b128 v[172:175], v250 offset:34816
	ds_read_b128 v[176:179], v250 offset:35840
	ds_read_b128 v[180:183], v250 offset:36864
	ds_read_b128 v[184:187], v250 offset:37888
	ds_read_b128 v[188:191], v250 offset:38912
	ds_read_b128 v[192:195], v250 offset:39936
	global_load_lds_dwordx4 v[204:205], off
	v_lshl_add_u64 v[204:205], s[14:15], 0, v[218:219]
	s_mov_b32 m0, s44
	s_nop 0
	global_load_lds_dwordx4 v[204:205], off
	s_waitcnt vmcnt(8)
	s_waitcnt lgkmcnt(0)
	s_barrier
	s_setprio 1
	s_waitcnt lgkmcnt(0)
	v_mfma_f32_16x16x32_bf16 v[128:131], v[132:135], v[164:167], v[128:131]
	v_mfma_f32_16x16x32_bf16 v[128:131], v[136:139], v[168:171], v[128:131]
	v_mfma_f32_16x16x32_bf16 v[124:127], v[140:143], v[164:167], v[124:127]
	v_mfma_f32_16x16x32_bf16 v[124:127], v[144:147], v[168:171], v[124:127]
	v_mfma_f32_16x16x32_bf16 v[112:115], v[132:135], v[172:175], v[112:115]
	v_mfma_f32_16x16x32_bf16 v[112:115], v[136:139], v[176:179], v[112:115]
	v_mfma_f32_16x16x32_bf16 v[108:111], v[140:143], v[172:175], v[108:111]
	v_mfma_f32_16x16x32_bf16 v[108:111], v[144:147], v[176:179], v[108:111]
	v_mfma_f32_16x16x32_bf16 v[96:99], v[132:135], v[180:183], v[96:99]
	v_mfma_f32_16x16x32_bf16 v[96:99], v[136:139], v[184:187], v[96:99]
	v_mfma_f32_16x16x32_bf16 v[92:95], v[140:143], v[180:183], v[92:95]
	v_mfma_f32_16x16x32_bf16 v[92:95], v[144:147], v[184:187], v[92:95]
	v_mfma_f32_16x16x32_bf16 v[80:83], v[132:135], v[188:191], v[80:83]
	v_mfma_f32_16x16x32_bf16 v[80:83], v[136:139], v[192:195], v[80:83]
	v_mfma_f32_16x16x32_bf16 v[76:79], v[140:143], v[188:191], v[76:79]
	v_mfma_f32_16x16x32_bf16 v[76:79], v[144:147], v[192:195], v[76:79]
	s_setprio 0
	s_setprio 1
	v_mfma_f32_16x16x32_bf16 v[120:123], v[148:151], v[164:167], v[120:123]
	v_mfma_f32_16x16x32_bf16 v[120:123], v[152:155], v[168:171], v[120:123]
	v_mfma_f32_16x16x32_bf16 v[116:119], v[156:159], v[164:167], v[116:119]
	v_mfma_f32_16x16x32_bf16 v[116:119], v[160:163], v[168:171], v[116:119]
	v_mfma_f32_16x16x32_bf16 v[104:107], v[148:151], v[172:175], v[104:107]
	v_mfma_f32_16x16x32_bf16 v[104:107], v[152:155], v[176:179], v[104:107]
	v_mfma_f32_16x16x32_bf16 v[100:103], v[156:159], v[172:175], v[100:103]
	v_mfma_f32_16x16x32_bf16 v[100:103], v[160:163], v[176:179], v[100:103]
	v_mfma_f32_16x16x32_bf16 v[88:91], v[148:151], v[180:183], v[88:91]
	v_mfma_f32_16x16x32_bf16 v[88:91], v[152:155], v[184:187], v[88:91]
	v_mfma_f32_16x16x32_bf16 v[84:87], v[156:159], v[180:183], v[84:87]
	v_mfma_f32_16x16x32_bf16 v[84:87], v[160:163], v[184:187], v[84:87]
	v_mfma_f32_16x16x32_bf16 v[72:75], v[148:151], v[188:191], v[72:75]
	v_mfma_f32_16x16x32_bf16 v[72:75], v[152:155], v[192:195], v[72:75]
	v_mfma_f32_16x16x32_bf16 v[68:71], v[156:159], v[188:191], v[68:71]
	v_mfma_f32_16x16x32_bf16 v[68:71], v[160:163], v[192:195], v[68:71]
	s_setprio 0
	s_barrier
	s_mov_b32 m0, s50
	v_lshl_add_u64 v[196:197], v[196:197], 0, s[64:65]
	s_add_u32 s14, s18, 0x160080
	ds_read_b128 v[164:167], v250 offset:49152
	ds_read_b128 v[168:171], v250 offset:50176
	ds_read_b128 v[172:175], v250 offset:51200
	ds_read_b128 v[176:179], v250 offset:52224
	ds_read_b128 v[180:183], v250 offset:53248
	ds_read_b128 v[184:187], v250 offset:54272
	ds_read_b128 v[188:191], v250 offset:55296
	ds_read_b128 v[192:195], v250 offset:56320
	global_load_lds_dwordx4 v[196:197], off
	v_lshl_add_u64 v[196:197], v[198:199], 0, s[64:65]
	s_mov_b32 m0, s51
	s_addc_u32 s15, s19, 0
	global_load_lds_dwordx4 v[196:197], off
	v_lshl_add_u64 v[196:197], s[14:15], 0, v[2:3]
	s_mov_b32 m0, s57
	s_nop 0
	global_load_lds_dwordx4 v[196:197], off
	v_lshl_add_u64 v[196:197], s[14:15], 0, v[216:217]
	s_mov_b32 m0, s58
	s_nop 0
	global_load_lds_dwordx4 v[196:197], off
	v_lshl_add_u64 v[196:197], v[200:201], 0, s[64:65]
	s_mov_b32 m0, s52
	s_nop 0
	global_load_lds_dwordx4 v[196:197], off
	v_lshl_add_u64 v[196:197], v[202:203], 0, s[64:65]
	s_mov_b32 m0, s53
	s_nop 0
	global_load_lds_dwordx4 v[196:197], off
	s_waitcnt vmcnt(8)
	s_waitcnt lgkmcnt(0)
	s_barrier
	s_setprio 1
	s_waitcnt lgkmcnt(0)
	v_mfma_f32_16x16x32_bf16 v[64:67], v[132:135], v[164:167], v[64:67]
	v_mfma_f32_16x16x32_bf16 v[64:67], v[136:139], v[168:171], v[64:67]
	v_mfma_f32_16x16x32_bf16 v[60:63], v[140:143], v[164:167], v[60:63]
	v_mfma_f32_16x16x32_bf16 v[60:63], v[144:147], v[168:171], v[60:63]
	v_mfma_f32_16x16x32_bf16 v[48:51], v[132:135], v[172:175], v[48:51]
	v_mfma_f32_16x16x32_bf16 v[48:51], v[136:139], v[176:179], v[48:51]
	v_mfma_f32_16x16x32_bf16 v[44:47], v[140:143], v[172:175], v[44:47]
	v_mfma_f32_16x16x32_bf16 v[44:47], v[144:147], v[176:179], v[44:47]
	v_mfma_f32_16x16x32_bf16 v[32:35], v[132:135], v[180:183], v[32:35]
	v_mfma_f32_16x16x32_bf16 v[32:35], v[136:139], v[184:187], v[32:35]
	v_mfma_f32_16x16x32_bf16 v[28:31], v[140:143], v[180:183], v[28:31]
	v_mfma_f32_16x16x32_bf16 v[28:31], v[144:147], v[184:187], v[28:31]
	v_mfma_f32_16x16x32_bf16 v[16:19], v[132:135], v[188:191], v[16:19]
	v_mfma_f32_16x16x32_bf16 v[16:19], v[136:139], v[192:195], v[16:19]
	v_mfma_f32_16x16x32_bf16 v[12:15], v[140:143], v[188:191], v[12:15]
	v_mfma_f32_16x16x32_bf16 v[12:15], v[144:147], v[192:195], v[12:15]
	s_setprio 0
	s_setprio 1
	v_mfma_f32_16x16x32_bf16 v[56:59], v[148:151], v[164:167], v[56:59]
	v_mfma_f32_16x16x32_bf16 v[56:59], v[152:155], v[168:171], v[56:59]
	v_mfma_f32_16x16x32_bf16 v[52:55], v[156:159], v[164:167], v[52:55]
	v_mfma_f32_16x16x32_bf16 v[52:55], v[160:163], v[168:171], v[52:55]
	v_mfma_f32_16x16x32_bf16 v[40:43], v[148:151], v[172:175], v[40:43]
	v_mfma_f32_16x16x32_bf16 v[40:43], v[152:155], v[176:179], v[40:43]
	v_mfma_f32_16x16x32_bf16 v[36:39], v[156:159], v[172:175], v[36:39]
	v_mfma_f32_16x16x32_bf16 v[36:39], v[160:163], v[176:179], v[36:39]
	v_mfma_f32_16x16x32_bf16 v[24:27], v[148:151], v[180:183], v[24:27]
	v_mfma_f32_16x16x32_bf16 v[24:27], v[152:155], v[184:187], v[24:27]
	v_mfma_f32_16x16x32_bf16 v[20:23], v[156:159], v[180:183], v[20:23]
	v_mfma_f32_16x16x32_bf16 v[20:23], v[160:163], v[184:187], v[20:23]
	v_mfma_f32_16x16x32_bf16 v[8:11], v[148:151], v[188:191], v[8:11]
	v_mfma_f32_16x16x32_bf16 v[8:11], v[152:155], v[192:195], v[8:11]
	v_mfma_f32_16x16x32_bf16 v[4:7], v[156:159], v[188:191], v[4:7]
	v_mfma_f32_16x16x32_bf16 v[4:7], v[160:163], v[192:195], v[4:7]
	s_setprio 0
	s_barrier
	s_add_i32 s74, s74, 2
	s_add_u32 s71, s71, 0x100
	s_addc_u32 s73, s73, 0
	s_cmpk_gt_u32 s74, 0x55
	s_mov_b64 s[14:15], s[24:25]
	s_cbranch_scc0 .LBB0_3195
	s_and_b64 vcc, exec, s[10:11]
	s_cbranch_vccz .LBB0_3198
	s_barrier
